# remove redundant post-barrier s_waitcnt lgkmcnt(0) ahead of every MFMA block
# baseline (speedup 1.0000x reference)
.LBB0_255:
	s_add_u32 s48, s46, 0xfffc0080
	s_addc_u32 s49, s47, -1
	s_add_i32 s62, 0, 0x10000
	s_cmp_eq_u32 s60, 12
	s_cselect_b32 s51, s41, s49
	s_cselect_b32 s50, s96, s48
	v_add_u32_e32 v138, s62, v142
	s_cselect_b32 s49, s35, vcc_hi
	s_cselect_b32 s48, s97, vcc_lo
	s_add_i32 s61, 0, 0x14000
	ds_read_b128 v[144:147], v138
	ds_read_b128 v[148:151], v138 offset:1024
	ds_read_b128 v[152:155], v138 offset:2048
	ds_read_b128 v[168:171], v138 offset:3072
	v_add_u32_e32 v138, s61, v142
	ds_read_b128 v[172:175], v138
	ds_read_b128 v[176:179], v138 offset:1024
	ds_read_b128 v[180:183], v138 offset:2048
	ds_read_b128 v[184:187], v138 offset:3072
	v_lshl_add_u64 v[138:139], s[46:47], 0, v[134:135]
	s_add_i32 m0, s65, 0xc000
	ds_read_b128 v[188:191], v143
	ds_read_b128 v[200:203], v143 offset:1024
	ds_read_b128 v[204:207], v143 offset:2048
	ds_read_b128 v[208:211], v143 offset:3072
	ds_read_b128 v[212:215], v143 offset:4096
	ds_read_b128 v[216:219], v143 offset:5120
	ds_read_b128 v[220:223], v143 offset:6144
	ds_read_b128 v[224:227], v143 offset:7168
	global_load_lds_dwordx4 v[138:139], off
	v_lshl_add_u64 v[138:139], s[46:47], 0, v[136:137]
	s_add_i32 m0, s65, 0xe000
	s_nop 0
	global_load_lds_dwordx4 v[138:139], off
	s_waitcnt vmcnt(8)
	s_waitcnt lgkmcnt(0)
	s_barrier
	s_setprio 1
	v_mfma_f32_16x16x32_bf16 v[124:127], v[144:147], v[188:191], v[124:127]
	v_mfma_f32_16x16x32_bf16 v[120:123], v[152:155], v[188:191], v[120:123]
	v_mfma_f32_16x16x32_bf16 v[108:111], v[144:147], v[204:207], v[108:111]
	v_mfma_f32_16x16x32_bf16 v[104:107], v[152:155], v[204:207], v[104:107]
	v_mfma_f32_16x16x32_bf16 v[92:95], v[144:147], v[212:215], v[92:95]
	v_mfma_f32_16x16x32_bf16 v[88:91], v[152:155], v[212:215], v[88:91]
	v_mfma_f32_16x16x32_bf16 v[76:79], v[144:147], v[220:223], v[76:79]
	v_mfma_f32_16x16x32_bf16 v[72:75], v[152:155], v[220:223], v[72:75]
	v_mfma_f32_16x16x32_bf16 v[124:127], v[148:151], v[200:203], v[124:127]
	v_mfma_f32_16x16x32_bf16 v[120:123], v[168:171], v[200:203], v[120:123]
	v_mfma_f32_16x16x32_bf16 v[108:111], v[148:151], v[208:211], v[108:111]
	v_mfma_f32_16x16x32_bf16 v[104:107], v[168:171], v[208:211], v[104:107]
	v_mfma_f32_16x16x32_bf16 v[92:95], v[148:151], v[216:219], v[92:95]
	v_mfma_f32_16x16x32_bf16 v[88:91], v[168:171], v[216:219], v[88:91]
	v_mfma_f32_16x16x32_bf16 v[76:79], v[148:151], v[224:227], v[76:79]
	v_mfma_f32_16x16x32_bf16 v[72:75], v[168:171], v[224:227], v[72:75]
	s_setprio 0
	s_setprio 1
	v_mfma_f32_16x16x32_bf16 v[116:119], v[172:175], v[188:191], v[116:119]
	v_mfma_f32_16x16x32_bf16 v[112:115], v[180:183], v[188:191], v[112:115]
	v_mfma_f32_16x16x32_bf16 v[100:103], v[172:175], v[204:207], v[100:103]
	v_mfma_f32_16x16x32_bf16 v[96:99], v[180:183], v[204:207], v[96:99]
	v_mfma_f32_16x16x32_bf16 v[84:87], v[172:175], v[212:215], v[84:87]
	v_mfma_f32_16x16x32_bf16 v[80:83], v[180:183], v[212:215], v[80:83]
	v_mfma_f32_16x16x32_bf16 v[68:71], v[172:175], v[220:223], v[68:71]
	v_mfma_f32_16x16x32_bf16 v[64:67], v[180:183], v[220:223], v[64:67]
	v_mfma_f32_16x16x32_bf16 v[116:119], v[176:179], v[200:203], v[116:119]
	v_mfma_f32_16x16x32_bf16 v[112:115], v[184:187], v[200:203], v[112:115]
	v_mfma_f32_16x16x32_bf16 v[100:103], v[176:179], v[208:211], v[100:103]
	v_mfma_f32_16x16x32_bf16 v[96:99], v[184:187], v[208:211], v[96:99]
	v_mfma_f32_16x16x32_bf16 v[84:87], v[176:179], v[216:219], v[84:87]
	v_mfma_f32_16x16x32_bf16 v[80:83], v[184:187], v[216:219], v[80:83]
	v_mfma_f32_16x16x32_bf16 v[68:71], v[176:179], v[224:227], v[68:71]
	v_mfma_f32_16x16x32_bf16 v[64:67], v[184:187], v[224:227], v[64:67]
	s_setprio 0
	s_barrier
	s_add_i32 s62, s62, s64
	v_lshl_add_u64 v[138:139], s[48:49], 0, v[158:159]
	s_mov_b32 m0, s62
	ds_read_b128 v[188:191], v143 offset:16384
	ds_read_b128 v[200:203], v143 offset:17408
	ds_read_b128 v[204:207], v143 offset:18432
	ds_read_b128 v[208:211], v143 offset:19456
	ds_read_b128 v[212:215], v143 offset:20480
	ds_read_b128 v[216:219], v143 offset:21504
	ds_read_b128 v[220:223], v143 offset:22528
	ds_read_b128 v[224:227], v143 offset:23552
	global_load_lds_dwordx4 v[138:139], off
	s_add_i32 m0, s62, 0x2000
	s_add_u32 s62, s48, 0x40000
	v_lshl_add_u64 v[192:193], s[48:49], 0, v[128:129]
	s_addc_u32 s63, s49, 0
	s_add_i32 s61, s61, s64
	global_load_lds_dwordx4 v[192:193], off
	v_lshl_add_u64 v[228:229], s[62:63], 0, v[158:159]
	s_mov_b32 m0, s61
	v_lshl_add_u64 v[230:231], s[50:51], 0, v[130:131]
	global_load_lds_dwordx4 v[228:229], off
	v_lshl_add_u64 v[228:229], s[62:63], 0, v[128:129]
	s_add_i32 m0, s61, 0x2000
	s_nop 0
	global_load_lds_dwordx4 v[228:229], off
	v_lshl_add_u64 v[228:229], s[50:51], 0, v[132:133]
	s_mov_b32 m0, s65
	s_nop 0
	global_load_lds_dwordx4 v[228:229], off
	s_mov_b32 m0, s82
	s_nop 0
	global_load_lds_dwordx4 v[230:231], off
	s_waitcnt vmcnt(8)
	s_waitcnt lgkmcnt(0)
	s_barrier
	s_setprio 1
	v_mfma_f32_16x16x32_bf16 v[60:63], v[144:147], v[188:191], v[60:63]
	v_mfma_f32_16x16x32_bf16 v[56:59], v[152:155], v[188:191], v[56:59]
	v_mfma_f32_16x16x32_bf16 v[44:47], v[144:147], v[204:207], v[44:47]
	v_mfma_f32_16x16x32_bf16 v[40:43], v[152:155], v[204:207], v[40:43]
	v_mfma_f32_16x16x32_bf16 v[28:31], v[144:147], v[212:215], v[28:31]
	v_mfma_f32_16x16x32_bf16 v[24:27], v[152:155], v[212:215], v[24:27]
	v_mfma_f32_16x16x32_bf16 v[12:15], v[144:147], v[220:223], v[12:15]
	v_mfma_f32_16x16x32_bf16 v[8:11], v[152:155], v[220:223], v[8:11]
	v_mfma_f32_16x16x32_bf16 v[60:63], v[148:151], v[200:203], v[60:63]
	v_mfma_f32_16x16x32_bf16 v[56:59], v[168:171], v[200:203], v[56:59]
	v_mfma_f32_16x16x32_bf16 v[44:47], v[148:151], v[208:211], v[44:47]
	v_mfma_f32_16x16x32_bf16 v[40:43], v[168:171], v[208:211], v[40:43]
	v_mfma_f32_16x16x32_bf16 v[28:31], v[148:151], v[216:219], v[28:31]
	v_mfma_f32_16x16x32_bf16 v[24:27], v[168:171], v[216:219], v[24:27]
	v_mfma_f32_16x16x32_bf16 v[12:15], v[148:151], v[224:227], v[12:15]
	v_mfma_f32_16x16x32_bf16 v[8:11], v[168:171], v[224:227], v[8:11]
	s_setprio 0
	s_setprio 1
	v_mfma_f32_16x16x32_bf16 v[52:55], v[172:175], v[188:191], v[52:55]
	v_mfma_f32_16x16x32_bf16 v[48:51], v[180:183], v[188:191], v[48:51]
	v_mfma_f32_16x16x32_bf16 v[36:39], v[172:175], v[204:207], v[36:39]
	v_mfma_f32_16x16x32_bf16 v[32:35], v[180:183], v[204:207], v[32:35]
	v_mfma_f32_16x16x32_bf16 v[20:23], v[172:175], v[212:215], v[20:23]
	v_mfma_f32_16x16x32_bf16 v[16:19], v[180:183], v[212:215], v[16:19]
	v_mfma_f32_16x16x32_bf16 v[4:7], v[172:175], v[220:223], v[4:7]
	v_mfma_f32_16x16x32_bf16 v[0:3], v[180:183], v[220:223], v[0:3]
	v_mfma_f32_16x16x32_bf16 v[52:55], v[176:179], v[200:203], v[52:55]
	v_mfma_f32_16x16x32_bf16 v[48:51], v[184:187], v[200:203], v[48:51]
	v_mfma_f32_16x16x32_bf16 v[36:39], v[176:179], v[208:211], v[36:39]
	v_mfma_f32_16x16x32_bf16 v[32:35], v[184:187], v[208:211], v[32:35]
	v_mfma_f32_16x16x32_bf16 v[20:23], v[176:179], v[216:219], v[20:23]
	v_mfma_f32_16x16x32_bf16 v[16:19], v[184:187], v[216:219], v[16:19]
	v_mfma_f32_16x16x32_bf16 v[4:7], v[176:179], v[224:227], v[4:7]
	v_mfma_f32_16x16x32_bf16 v[0:3], v[184:187], v[224:227], v[0:3]
	s_setprio 0
	s_barrier
	s_add_i32 s61, 0, 0x18000
	s_add_i32 s62, 0, 0x1c000
	v_add_u32_e32 v168, s61, v142
	v_add_u32_e32 v184, s62, v142
	ds_read_b128 v[144:147], v168
	ds_read_b128 v[148:151], v168 offset:1024
	ds_read_b128 v[152:155], v168 offset:2048
	ds_read_b128 v[168:171], v168 offset:3072
	ds_read_b128 v[172:175], v184
	ds_read_b128 v[176:179], v184 offset:1024
	ds_read_b128 v[180:183], v184 offset:2048
	ds_read_b128 v[184:187], v184 offset:3072
	s_add_u32 s50, s50, 0x40000
	s_addc_u32 s51, s51, 0
	s_mov_b32 m0, s83
	v_lshl_add_u64 v[232:233], s[50:51], 0, v[132:133]
	ds_read_b128 v[188:191], v143 offset:32768
	ds_read_b128 v[200:203], v143 offset:33792
	ds_read_b128 v[204:207], v143 offset:34816
	ds_read_b128 v[208:211], v143 offset:35840
	ds_read_b128 v[212:215], v143 offset:36864
	ds_read_b128 v[216:219], v143 offset:37888
	ds_read_b128 v[220:223], v143 offset:38912
	ds_read_b128 v[224:227], v143 offset:39936
	global_load_lds_dwordx4 v[232:233], off
	v_lshl_add_u64 v[232:233], s[50:51], 0, v[130:131]
	s_mov_b32 m0, s84
	s_nop 0
	global_load_lds_dwordx4 v[232:233], off
	s_waitcnt vmcnt(8)
	s_waitcnt lgkmcnt(0)
	s_barrier
	s_setprio 1
	v_mfma_f32_16x16x32_bf16 v[124:127], v[144:147], v[188:191], v[124:127]
	v_mfma_f32_16x16x32_bf16 v[120:123], v[152:155], v[188:191], v[120:123]
	v_mfma_f32_16x16x32_bf16 v[108:111], v[144:147], v[204:207], v[108:111]
	v_mfma_f32_16x16x32_bf16 v[104:107], v[152:155], v[204:207], v[104:107]
	v_mfma_f32_16x16x32_bf16 v[92:95], v[144:147], v[212:215], v[92:95]
	v_mfma_f32_16x16x32_bf16 v[88:91], v[152:155], v[212:215], v[88:91]
	v_mfma_f32_16x16x32_bf16 v[76:79], v[144:147], v[220:223], v[76:79]
	v_mfma_f32_16x16x32_bf16 v[72:75], v[152:155], v[220:223], v[72:75]
	v_mfma_f32_16x16x32_bf16 v[124:127], v[148:151], v[200:203], v[124:127]
	v_mfma_f32_16x16x32_bf16 v[120:123], v[168:171], v[200:203], v[120:123]
	v_mfma_f32_16x16x32_bf16 v[108:111], v[148:151], v[208:211], v[108:111]
	v_mfma_f32_16x16x32_bf16 v[104:107], v[168:171], v[208:211], v[104:107]
	v_mfma_f32_16x16x32_bf16 v[92:95], v[148:151], v[216:219], v[92:95]
	v_mfma_f32_16x16x32_bf16 v[88:91], v[168:171], v[216:219], v[88:91]
	v_mfma_f32_16x16x32_bf16 v[76:79], v[148:151], v[224:227], v[76:79]
	v_mfma_f32_16x16x32_bf16 v[72:75], v[168:171], v[224:227], v[72:75]
	s_setprio 0
	s_setprio 1
	v_mfma_f32_16x16x32_bf16 v[116:119], v[172:175], v[188:191], v[116:119]
	v_mfma_f32_16x16x32_bf16 v[112:115], v[180:183], v[188:191], v[112:115]
	v_mfma_f32_16x16x32_bf16 v[100:103], v[172:175], v[204:207], v[100:103]
	v_mfma_f32_16x16x32_bf16 v[96:99], v[180:183], v[204:207], v[96:99]
	v_mfma_f32_16x16x32_bf16 v[84:87], v[172:175], v[212:215], v[84:87]
	v_mfma_f32_16x16x32_bf16 v[80:83], v[180:183], v[212:215], v[80:83]
	v_mfma_f32_16x16x32_bf16 v[68:71], v[172:175], v[220:223], v[68:71]
	v_mfma_f32_16x16x32_bf16 v[64:67], v[180:183], v[220:223], v[64:67]
	v_mfma_f32_16x16x32_bf16 v[116:119], v[176:179], v[200:203], v[116:119]
	v_mfma_f32_16x16x32_bf16 v[112:115], v[184:187], v[200:203], v[112:115]
	v_mfma_f32_16x16x32_bf16 v[100:103], v[176:179], v[208:211], v[100:103]
	v_mfma_f32_16x16x32_bf16 v[96:99], v[184:187], v[208:211], v[96:99]
	v_mfma_f32_16x16x32_bf16 v[84:87], v[176:179], v[216:219], v[84:87]
	v_mfma_f32_16x16x32_bf16 v[80:83], v[184:187], v[216:219], v[80:83]
	v_mfma_f32_16x16x32_bf16 v[68:71], v[176:179], v[224:227], v[68:71]
	v_mfma_f32_16x16x32_bf16 v[64:67], v[184:187], v[224:227], v[64:67]
	s_setprio 0
	s_barrier
	s_add_i32 s50, s61, s64
	v_lshl_add_u64 v[138:139], v[138:139], 0, s[14:15]
	s_mov_b32 m0, s50
	ds_read_b128 v[188:191], v143 offset:49152
	ds_read_b128 v[200:203], v143 offset:50176
	ds_read_b128 v[204:207], v143 offset:51200
	ds_read_b128 v[208:211], v143 offset:52224
	ds_read_b128 v[212:215], v143 offset:53248
	ds_read_b128 v[216:219], v143 offset:54272
	ds_read_b128 v[220:223], v143 offset:55296
	ds_read_b128 v[224:227], v143 offset:56320
	global_load_lds_dwordx4 v[138:139], off
	s_add_i32 m0, s50, 0x2000
	s_add_u32 s48, s48, 0x40080
	v_lshl_add_u64 v[138:139], v[192:193], 0, s[14:15]
	s_addc_u32 s49, s49, 0
	s_add_i32 s50, s62, s64
	global_load_lds_dwordx4 v[138:139], off
	v_lshl_add_u64 v[138:139], s[48:49], 0, v[158:159]
	s_mov_b32 m0, s50
	s_nop 0
	global_load_lds_dwordx4 v[138:139], off
	v_lshl_add_u64 v[138:139], s[48:49], 0, v[128:129]
	s_add_i32 m0, s50, 0x2000
	s_nop 0
	global_load_lds_dwordx4 v[138:139], off
	v_lshl_add_u64 v[138:139], v[228:229], 0, s[14:15]
	s_mov_b32 m0, s87
	s_nop 0
	global_load_lds_dwordx4 v[138:139], off
	v_lshl_add_u64 v[138:139], v[230:231], 0, s[14:15]
	s_mov_b32 m0, s88
	s_nop 0
	global_load_lds_dwordx4 v[138:139], off
	s_waitcnt vmcnt(8)
	s_waitcnt lgkmcnt(0)
	s_barrier
	s_setprio 1
	v_mfma_f32_16x16x32_bf16 v[60:63], v[144:147], v[188:191], v[60:63]
	v_mfma_f32_16x16x32_bf16 v[56:59], v[152:155], v[188:191], v[56:59]
	v_mfma_f32_16x16x32_bf16 v[44:47], v[144:147], v[204:207], v[44:47]
	v_mfma_f32_16x16x32_bf16 v[40:43], v[152:155], v[204:207], v[40:43]
	v_mfma_f32_16x16x32_bf16 v[28:31], v[144:147], v[212:215], v[28:31]
	v_mfma_f32_16x16x32_bf16 v[24:27], v[152:155], v[212:215], v[24:27]
	v_mfma_f32_16x16x32_bf16 v[12:15], v[144:147], v[220:223], v[12:15]
	v_mfma_f32_16x16x32_bf16 v[8:11], v[152:155], v[220:223], v[8:11]
	v_mfma_f32_16x16x32_bf16 v[60:63], v[148:151], v[200:203], v[60:63]
	v_mfma_f32_16x16x32_bf16 v[56:59], v[168:171], v[200:203], v[56:59]
	v_mfma_f32_16x16x32_bf16 v[44:47], v[148:151], v[208:211], v[44:47]
	v_mfma_f32_16x16x32_bf16 v[40:43], v[168:171], v[208:211], v[40:43]
	v_mfma_f32_16x16x32_bf16 v[28:31], v[148:151], v[216:219], v[28:31]
	v_mfma_f32_16x16x32_bf16 v[24:27], v[168:171], v[216:219], v[24:27]
	v_mfma_f32_16x16x32_bf16 v[12:15], v[148:151], v[224:227], v[12:15]
	v_mfma_f32_16x16x32_bf16 v[8:11], v[168:171], v[224:227], v[8:11]
	s_setprio 0
	s_setprio 1
	v_mfma_f32_16x16x32_bf16 v[52:55], v[172:175], v[188:191], v[52:55]
	v_mfma_f32_16x16x32_bf16 v[48:51], v[180:183], v[188:191], v[48:51]
	v_mfma_f32_16x16x32_bf16 v[36:39], v[172:175], v[204:207], v[36:39]
	v_mfma_f32_16x16x32_bf16 v[32:35], v[180:183], v[204:207], v[32:35]
	v_mfma_f32_16x16x32_bf16 v[20:23], v[172:175], v[212:215], v[20:23]
	v_mfma_f32_16x16x32_bf16 v[16:19], v[180:183], v[212:215], v[16:19]
	v_mfma_f32_16x16x32_bf16 v[4:7], v[172:175], v[220:223], v[4:7]
	v_mfma_f32_16x16x32_bf16 v[0:3], v[180:183], v[220:223], v[0:3]
	v_mfma_f32_16x16x32_bf16 v[52:55], v[176:179], v[200:203], v[52:55]
	v_mfma_f32_16x16x32_bf16 v[48:51], v[184:187], v[200:203], v[48:51]
	v_mfma_f32_16x16x32_bf16 v[36:39], v[176:179], v[208:211], v[36:39]
	v_mfma_f32_16x16x32_bf16 v[32:35], v[184:187], v[208:211], v[32:35]
	v_mfma_f32_16x16x32_bf16 v[20:23], v[176:179], v[216:219], v[20:23]
	v_mfma_f32_16x16x32_bf16 v[16:19], v[184:187], v[216:219], v[16:19]
	v_mfma_f32_16x16x32_bf16 v[4:7], v[176:179], v[224:227], v[4:7]
	v_mfma_f32_16x16x32_bf16 v[0:3], v[184:187], v[224:227], v[0:3]
	s_setprio 0
	s_barrier
	s_add_i32 s60, s60, 2
	s_add_u32 s46, s46, 0x100
	s_addc_u32 s47, s47, 0
	s_add_u32 vcc_lo, vcc_lo, 0x100
	s_addc_u32 vcc_hi, vcc_hi, 0
	s_cmp_gt_u32 s60, 13
	s_cbranch_scc0 .LBB0_255
	s_and_b64 vcc, exec, s[24:25]
	s_cbranch_vccz .LBB0_258
	s_barrier

.LBB0_280:
	s_add_u32 s42, s40, 0xfffc0080
	s_addc_u32 s43, s41, -1
	s_add_i32 s62, 0, 0x10000
	s_cmp_eq_u32 vcc_lo, 12
	s_cselect_b32 s45, s35, s43
	s_cselect_b32 s44, s48, s42
	v_add_u32_e32 v158, s62, v154
	s_cselect_b32 s43, s17, s65
	s_cselect_b32 s42, s49, s64
	s_add_i32 vcc_hi, 0, 0x14000
	ds_read_b128 v[140:143], v158
	ds_read_b128 v[144:147], v158 offset:1024
	ds_read_b128 v[148:151], v158 offset:2048
	ds_read_b128 v[168:171], v158 offset:3072
	v_add_u32_e32 v158, vcc_hi, v154
	ds_read_b128 v[172:175], v158
	ds_read_b128 v[176:179], v158 offset:1024
	ds_read_b128 v[180:183], v158 offset:2048
	ds_read_b128 v[184:187], v158 offset:3072
	v_lshl_add_u64 v[192:193], s[40:41], 0, v[136:137]
	s_add_i32 m0, s83, 0xc000
	ds_read_b128 v[188:191], v155
	ds_read_b128 v[200:203], v155 offset:1024
	ds_read_b128 v[204:207], v155 offset:2048
	ds_read_b128 v[208:211], v155 offset:3072
	ds_read_b128 v[212:215], v155 offset:4096
	ds_read_b128 v[216:219], v155 offset:5120
	ds_read_b128 v[220:223], v155 offset:6144
	ds_read_b128 v[224:227], v155 offset:7168
	global_load_lds_dwordx4 v[192:193], off
	v_lshl_add_u64 v[192:193], s[40:41], 0, v[138:139]
	s_add_i32 m0, s83, 0xe000
	s_nop 0
	global_load_lds_dwordx4 v[192:193], off
	s_waitcnt vmcnt(8)
	s_waitcnt lgkmcnt(0)
	s_barrier
	s_setprio 1
	v_mfma_f32_16x16x32_bf16 v[124:127], v[140:143], v[188:191], v[124:127]
	v_mfma_f32_16x16x32_bf16 v[120:123], v[148:151], v[188:191], v[120:123]
	v_mfma_f32_16x16x32_bf16 v[108:111], v[140:143], v[204:207], v[108:111]
	v_mfma_f32_16x16x32_bf16 v[104:107], v[148:151], v[204:207], v[104:107]
	v_mfma_f32_16x16x32_bf16 v[92:95], v[140:143], v[212:215], v[92:95]
	v_mfma_f32_16x16x32_bf16 v[88:91], v[148:151], v[212:215], v[88:91]
	v_mfma_f32_16x16x32_bf16 v[76:79], v[140:143], v[220:223], v[76:79]
	v_mfma_f32_16x16x32_bf16 v[72:75], v[148:151], v[220:223], v[72:75]
	v_mfma_f32_16x16x32_bf16 v[124:127], v[144:147], v[200:203], v[124:127]
	v_mfma_f32_16x16x32_bf16 v[120:123], v[168:171], v[200:203], v[120:123]
	v_mfma_f32_16x16x32_bf16 v[108:111], v[144:147], v[208:211], v[108:111]
	v_mfma_f32_16x16x32_bf16 v[104:107], v[168:171], v[208:211], v[104:107]
	v_mfma_f32_16x16x32_bf16 v[92:95], v[144:147], v[216:219], v[92:95]
	v_mfma_f32_16x16x32_bf16 v[88:91], v[168:171], v[216:219], v[88:91]
	v_mfma_f32_16x16x32_bf16 v[76:79], v[144:147], v[224:227], v[76:79]
	v_mfma_f32_16x16x32_bf16 v[72:75], v[168:171], v[224:227], v[72:75]
	s_setprio 0
	s_setprio 1
	v_mfma_f32_16x16x32_bf16 v[116:119], v[172:175], v[188:191], v[116:119]
	v_mfma_f32_16x16x32_bf16 v[112:115], v[180:183], v[188:191], v[112:115]
	v_mfma_f32_16x16x32_bf16 v[100:103], v[172:175], v[204:207], v[100:103]
	v_mfma_f32_16x16x32_bf16 v[96:99], v[180:183], v[204:207], v[96:99]
	v_mfma_f32_16x16x32_bf16 v[84:87], v[172:175], v[212:215], v[84:87]
	v_mfma_f32_16x16x32_bf16 v[80:83], v[180:183], v[212:215], v[80:83]
	v_mfma_f32_16x16x32_bf16 v[68:71], v[172:175], v[220:223], v[68:71]
	v_mfma_f32_16x16x32_bf16 v[64:67], v[180:183], v[220:223], v[64:67]
	v_mfma_f32_16x16x32_bf16 v[116:119], v[176:179], v[200:203], v[116:119]
	v_mfma_f32_16x16x32_bf16 v[112:115], v[184:187], v[200:203], v[112:115]
	v_mfma_f32_16x16x32_bf16 v[100:103], v[176:179], v[208:211], v[100:103]
	v_mfma_f32_16x16x32_bf16 v[96:99], v[184:187], v[208:211], v[96:99]
	v_mfma_f32_16x16x32_bf16 v[84:87], v[176:179], v[216:219], v[84:87]
	v_mfma_f32_16x16x32_bf16 v[80:83], v[184:187], v[216:219], v[80:83]
	v_mfma_f32_16x16x32_bf16 v[68:71], v[176:179], v[224:227], v[68:71]
	v_mfma_f32_16x16x32_bf16 v[64:67], v[184:187], v[224:227], v[64:67]
	s_setprio 0
	s_barrier
	s_add_i32 s62, s62, s82
	v_lshl_add_u64 v[192:193], s[42:43], 0, v[132:133]
	s_mov_b32 m0, s62
	ds_read_b128 v[188:191], v155 offset:16384
	ds_read_b128 v[200:203], v155 offset:17408
	ds_read_b128 v[204:207], v155 offset:18432
	ds_read_b128 v[208:211], v155 offset:19456
	ds_read_b128 v[212:215], v155 offset:20480
	ds_read_b128 v[216:219], v155 offset:21504
	ds_read_b128 v[220:223], v155 offset:22528
	ds_read_b128 v[224:227], v155 offset:23552
	global_load_lds_dwordx4 v[192:193], off
	s_add_i32 m0, s62, 0x2000
	s_add_u32 s62, s42, 0x40000
	v_lshl_add_u64 v[228:229], s[42:43], 0, v[128:129]
	s_addc_u32 s63, s43, 0
	s_add_i32 vcc_hi, vcc_hi, s82
	global_load_lds_dwordx4 v[228:229], off
	v_lshl_add_u64 v[230:231], s[62:63], 0, v[132:133]
	s_mov_b32 m0, vcc_hi
	v_lshl_add_u64 v[232:233], s[44:45], 0, v[130:131]
	global_load_lds_dwordx4 v[230:231], off
	v_lshl_add_u64 v[230:231], s[62:63], 0, v[128:129]
	s_add_i32 m0, vcc_hi, 0x2000
	s_nop 0
	global_load_lds_dwordx4 v[230:231], off
	v_lshl_add_u64 v[230:231], s[44:45], 0, v[134:135]
	s_mov_b32 m0, s83
	s_nop 0
	global_load_lds_dwordx4 v[230:231], off
	s_mov_b32 m0, s84
	s_nop 0
	global_load_lds_dwordx4 v[232:233], off
	s_waitcnt vmcnt(8)
	s_waitcnt lgkmcnt(0)
	s_barrier
	s_setprio 1
	v_mfma_f32_16x16x32_bf16 v[60:63], v[140:143], v[188:191], v[60:63]
	v_mfma_f32_16x16x32_bf16 v[56:59], v[148:151], v[188:191], v[56:59]
	v_mfma_f32_16x16x32_bf16 v[44:47], v[140:143], v[204:207], v[44:47]
	v_mfma_f32_16x16x32_bf16 v[40:43], v[148:151], v[204:207], v[40:43]
	v_mfma_f32_16x16x32_bf16 v[28:31], v[140:143], v[212:215], v[28:31]
	v_mfma_f32_16x16x32_bf16 v[24:27], v[148:151], v[212:215], v[24:27]
	v_mfma_f32_16x16x32_bf16 v[12:15], v[140:143], v[220:223], v[12:15]
	v_mfma_f32_16x16x32_bf16 v[8:11], v[148:151], v[220:223], v[8:11]
	v_mfma_f32_16x16x32_bf16 v[60:63], v[144:147], v[200:203], v[60:63]
	v_mfma_f32_16x16x32_bf16 v[56:59], v[168:171], v[200:203], v[56:59]
	v_mfma_f32_16x16x32_bf16 v[44:47], v[144:147], v[208:211], v[44:47]
	v_mfma_f32_16x16x32_bf16 v[40:43], v[168:171], v[208:211], v[40:43]
	v_mfma_f32_16x16x32_bf16 v[28:31], v[144:147], v[216:219], v[28:31]
	v_mfma_f32_16x16x32_bf16 v[24:27], v[168:171], v[216:219], v[24:27]
	v_mfma_f32_16x16x32_bf16 v[12:15], v[144:147], v[224:227], v[12:15]
	v_mfma_f32_16x16x32_bf16 v[8:11], v[168:171], v[224:227], v[8:11]
	s_setprio 0
	s_setprio 1
	v_mfma_f32_16x16x32_bf16 v[52:55], v[172:175], v[188:191], v[52:55]
	v_mfma_f32_16x16x32_bf16 v[48:51], v[180:183], v[188:191], v[48:51]
	v_mfma_f32_16x16x32_bf16 v[36:39], v[172:175], v[204:207], v[36:39]
	v_mfma_f32_16x16x32_bf16 v[32:35], v[180:183], v[204:207], v[32:35]
	v_mfma_f32_16x16x32_bf16 v[20:23], v[172:175], v[212:215], v[20:23]
	v_mfma_f32_16x16x32_bf16 v[16:19], v[180:183], v[212:215], v[16:19]
	v_mfma_f32_16x16x32_bf16 v[4:7], v[172:175], v[220:223], v[4:7]
	v_mfma_f32_16x16x32_bf16 v[0:3], v[180:183], v[220:223], v[0:3]
	v_mfma_f32_16x16x32_bf16 v[52:55], v[176:179], v[200:203], v[52:55]
	v_mfma_f32_16x16x32_bf16 v[48:51], v[184:187], v[200:203], v[48:51]
	v_mfma_f32_16x16x32_bf16 v[36:39], v[176:179], v[208:211], v[36:39]
	v_mfma_f32_16x16x32_bf16 v[32:35], v[184:187], v[208:211], v[32:35]
	v_mfma_f32_16x16x32_bf16 v[20:23], v[176:179], v[216:219], v[20:23]
	v_mfma_f32_16x16x32_bf16 v[16:19], v[184:187], v[216:219], v[16:19]
	v_mfma_f32_16x16x32_bf16 v[4:7], v[176:179], v[224:227], v[4:7]
	v_mfma_f32_16x16x32_bf16 v[0:3], v[184:187], v[224:227], v[0:3]
	s_setprio 0
	s_barrier
	s_add_i32 s62, 0, 0x18000
	v_add_u32_e32 v158, s62, v154
	s_add_i32 s63, 0, 0x1c000
	ds_read_b128 v[140:143], v158
	ds_read_b128 v[144:147], v158 offset:1024
	ds_read_b128 v[148:151], v158 offset:2048
	ds_read_b128 v[168:171], v158 offset:3072
	v_add_u32_e32 v158, s63, v154
	ds_read_b128 v[172:175], v158
	ds_read_b128 v[176:179], v158 offset:1024
	ds_read_b128 v[180:183], v158 offset:2048
	ds_read_b128 v[184:187], v158 offset:3072
	s_add_u32 s44, s44, 0x40000
	s_addc_u32 s45, s45, 0
	s_mov_b32 m0, s85
	v_lshl_add_u64 v[234:235], s[44:45], 0, v[134:135]
	ds_read_b128 v[188:191], v155 offset:32768
	ds_read_b128 v[200:203], v155 offset:33792
	ds_read_b128 v[204:207], v155 offset:34816
	ds_read_b128 v[208:211], v155 offset:35840
	ds_read_b128 v[212:215], v155 offset:36864
	ds_read_b128 v[216:219], v155 offset:37888
	ds_read_b128 v[220:223], v155 offset:38912
	ds_read_b128 v[224:227], v155 offset:39936
	global_load_lds_dwordx4 v[234:235], off
	v_lshl_add_u64 v[234:235], s[44:45], 0, v[130:131]
	s_mov_b32 m0, s86
	s_nop 0
	global_load_lds_dwordx4 v[234:235], off
	s_waitcnt vmcnt(8)
	s_waitcnt lgkmcnt(0)
	s_barrier
	s_setprio 1
	v_mfma_f32_16x16x32_bf16 v[124:127], v[140:143], v[188:191], v[124:127]
	v_mfma_f32_16x16x32_bf16 v[120:123], v[148:151], v[188:191], v[120:123]
	v_mfma_f32_16x16x32_bf16 v[108:111], v[140:143], v[204:207], v[108:111]
	v_mfma_f32_16x16x32_bf16 v[104:107], v[148:151], v[204:207], v[104:107]
	v_mfma_f32_16x16x32_bf16 v[92:95], v[140:143], v[212:215], v[92:95]
	v_mfma_f32_16x16x32_bf16 v[88:91], v[148:151], v[212:215], v[88:91]
	v_mfma_f32_16x16x32_bf16 v[76:79], v[140:143], v[220:223], v[76:79]
	v_mfma_f32_16x16x32_bf16 v[72:75], v[148:151], v[220:223], v[72:75]
	v_mfma_f32_16x16x32_bf16 v[124:127], v[144:147], v[200:203], v[124:127]
	v_mfma_f32_16x16x32_bf16 v[120:123], v[168:171], v[200:203], v[120:123]
	v_mfma_f32_16x16x32_bf16 v[108:111], v[144:147], v[208:211], v[108:111]
	v_mfma_f32_16x16x32_bf16 v[104:107], v[168:171], v[208:211], v[104:107]
	v_mfma_f32_16x16x32_bf16 v[92:95], v[144:147], v[216:219], v[92:95]
	v_mfma_f32_16x16x32_bf16 v[88:91], v[168:171], v[216:219], v[88:91]
	v_mfma_f32_16x16x32_bf16 v[76:79], v[144:147], v[224:227], v[76:79]
	v_mfma_f32_16x16x32_bf16 v[72:75], v[168:171], v[224:227], v[72:75]
	s_setprio 0
	s_setprio 1
	v_mfma_f32_16x16x32_bf16 v[116:119], v[172:175], v[188:191], v[116:119]
	v_mfma_f32_16x16x32_bf16 v[112:115], v[180:183], v[188:191], v[112:115]
	v_mfma_f32_16x16x32_bf16 v[100:103], v[172:175], v[204:207], v[100:103]
	v_mfma_f32_16x16x32_bf16 v[96:99], v[180:183], v[204:207], v[96:99]
	v_mfma_f32_16x16x32_bf16 v[84:87], v[172:175], v[212:215], v[84:87]
	v_mfma_f32_16x16x32_bf16 v[80:83], v[180:183], v[212:215], v[80:83]
	v_mfma_f32_16x16x32_bf16 v[68:71], v[172:175], v[220:223], v[68:71]
	v_mfma_f32_16x16x32_bf16 v[64:67], v[180:183], v[220:223], v[64:67]
	v_mfma_f32_16x16x32_bf16 v[116:119], v[176:179], v[200:203], v[116:119]
	v_mfma_f32_16x16x32_bf16 v[112:115], v[184:187], v[200:203], v[112:115]
	v_mfma_f32_16x16x32_bf16 v[100:103], v[176:179], v[208:211], v[100:103]
	v_mfma_f32_16x16x32_bf16 v[96:99], v[184:187], v[208:211], v[96:99]
	v_mfma_f32_16x16x32_bf16 v[84:87], v[176:179], v[216:219], v[84:87]
	v_mfma_f32_16x16x32_bf16 v[80:83], v[184:187], v[216:219], v[80:83]
	v_mfma_f32_16x16x32_bf16 v[68:71], v[176:179], v[224:227], v[68:71]
	v_mfma_f32_16x16x32_bf16 v[64:67], v[184:187], v[224:227], v[64:67]
	s_setprio 0
	s_barrier
	s_add_i32 s44, s62, s82
	v_lshl_add_u64 v[192:193], v[192:193], 0, s[14:15]
	s_mov_b32 m0, s44
	ds_read_b128 v[188:191], v155 offset:49152
	ds_read_b128 v[200:203], v155 offset:50176
	ds_read_b128 v[204:207], v155 offset:51200
	ds_read_b128 v[208:211], v155 offset:52224
	ds_read_b128 v[212:215], v155 offset:53248
	ds_read_b128 v[216:219], v155 offset:54272
	ds_read_b128 v[220:223], v155 offset:55296
	ds_read_b128 v[224:227], v155 offset:56320
	global_load_lds_dwordx4 v[192:193], off
	s_add_i32 m0, s44, 0x2000
	s_add_u32 s42, s42, 0x40080
	v_lshl_add_u64 v[192:193], v[228:229], 0, s[14:15]
	s_addc_u32 s43, s43, 0
	s_add_i32 s44, s63, s82
	global_load_lds_dwordx4 v[192:193], off
	v_lshl_add_u64 v[192:193], s[42:43], 0, v[132:133]
	s_mov_b32 m0, s44
	s_nop 0
	global_load_lds_dwordx4 v[192:193], off
	v_lshl_add_u64 v[192:193], s[42:43], 0, v[128:129]
	s_add_i32 m0, s44, 0x2000
	s_nop 0
	global_load_lds_dwordx4 v[192:193], off
	v_lshl_add_u64 v[192:193], v[230:231], 0, s[14:15]
	s_mov_b32 m0, s89
	s_nop 0
	global_load_lds_dwordx4 v[192:193], off
	v_lshl_add_u64 v[192:193], v[232:233], 0, s[14:15]
	s_mov_b32 m0, s90
	s_nop 0
	global_load_lds_dwordx4 v[192:193], off
	s_waitcnt vmcnt(8)
	s_waitcnt lgkmcnt(0)
	s_barrier
	s_setprio 1
	v_mfma_f32_16x16x32_bf16 v[60:63], v[140:143], v[188:191], v[60:63]
	v_mfma_f32_16x16x32_bf16 v[56:59], v[148:151], v[188:191], v[56:59]
	v_mfma_f32_16x16x32_bf16 v[44:47], v[140:143], v[204:207], v[44:47]
	v_mfma_f32_16x16x32_bf16 v[40:43], v[148:151], v[204:207], v[40:43]
	v_mfma_f32_16x16x32_bf16 v[28:31], v[140:143], v[212:215], v[28:31]
	v_mfma_f32_16x16x32_bf16 v[24:27], v[148:151], v[212:215], v[24:27]
	v_mfma_f32_16x16x32_bf16 v[12:15], v[140:143], v[220:223], v[12:15]
	v_mfma_f32_16x16x32_bf16 v[8:11], v[148:151], v[220:223], v[8:11]
	v_mfma_f32_16x16x32_bf16 v[60:63], v[144:147], v[200:203], v[60:63]
	v_mfma_f32_16x16x32_bf16 v[56:59], v[168:171], v[200:203], v[56:59]
	v_mfma_f32_16x16x32_bf16 v[44:47], v[144:147], v[208:211], v[44:47]
	v_mfma_f32_16x16x32_bf16 v[40:43], v[168:171], v[208:211], v[40:43]
	v_mfma_f32_16x16x32_bf16 v[28:31], v[144:147], v[216:219], v[28:31]
	v_mfma_f32_16x16x32_bf16 v[24:27], v[168:171], v[216:219], v[24:27]
	v_mfma_f32_16x16x32_bf16 v[12:15], v[144:147], v[224:227], v[12:15]
	v_mfma_f32_16x16x32_bf16 v[8:11], v[168:171], v[224:227], v[8:11]
	s_setprio 0
	s_setprio 1
	v_mfma_f32_16x16x32_bf16 v[52:55], v[172:175], v[188:191], v[52:55]
	v_mfma_f32_16x16x32_bf16 v[48:51], v[180:183], v[188:191], v[48:51]
	v_mfma_f32_16x16x32_bf16 v[36:39], v[172:175], v[204:207], v[36:39]
	v_mfma_f32_16x16x32_bf16 v[32:35], v[180:183], v[204:207], v[32:35]
	v_mfma_f32_16x16x32_bf16 v[20:23], v[172:175], v[212:215], v[20:23]
	v_mfma_f32_16x16x32_bf16 v[16:19], v[180:183], v[212:215], v[16:19]
	v_mfma_f32_16x16x32_bf16 v[4:7], v[172:175], v[220:223], v[4:7]
	v_mfma_f32_16x16x32_bf16 v[0:3], v[180:183], v[220:223], v[0:3]
	v_mfma_f32_16x16x32_bf16 v[52:55], v[176:179], v[200:203], v[52:55]
	v_mfma_f32_16x16x32_bf16 v[48:51], v[184:187], v[200:203], v[48:51]
	v_mfma_f32_16x16x32_bf16 v[36:39], v[176:179], v[208:211], v[36:39]
	v_mfma_f32_16x16x32_bf16 v[32:35], v[184:187], v[208:211], v[32:35]
	v_mfma_f32_16x16x32_bf16 v[20:23], v[176:179], v[216:219], v[20:23]
	v_mfma_f32_16x16x32_bf16 v[16:19], v[184:187], v[216:219], v[16:19]
	v_mfma_f32_16x16x32_bf16 v[4:7], v[176:179], v[224:227], v[4:7]
	v_mfma_f32_16x16x32_bf16 v[0:3], v[184:187], v[224:227], v[0:3]
	s_setprio 0
	s_barrier
	s_add_i32 vcc_lo, vcc_lo, 2
	s_add_u32 s40, s40, 0x100
	s_addc_u32 s41, s41, 0
	s_add_u32 s64, s64, 0x100
	s_addc_u32 s65, s65, 0
	s_cmp_gt_u32 vcc_lo, 13
	s_cbranch_scc0 .LBB0_280
	s_and_b64 vcc, exec, s[6:7]
	s_cbranch_vccz .LBB0_283
	s_barrier

.LBB0_496:
	s_add_u32 s2, s2, 0x80
	s_addc_u32 s3, s3, 0
	s_add_u32 s40, s34, 0x100
	s_addc_u32 s41, s35, 0
	s_mov_b32 s34, 0
	s_waitcnt lgkmcnt(0)
	s_waitcnt vmcnt(0)
	s_add_i32 s86, s34, 2
	s_add_u32 s62, s2, 0x80
	s_addc_u32 s35, s3, 0
	s_add_i32 s63, 0, 0x10000
	s_cmp_eq_u32 s80, s34
	s_cselect_b32 s35, s17, s35
	s_cselect_b32 s34, s16, s62
	s_cselect_b32 s89, s25, s41
	s_cselect_b32 s88, s24, s40
	s_add_i32 s62, 0, 0x14000
	v_add_u32_e32 v140, s63, v201
	v_add_u32_e32 v180, s62, v201
	ds_read_b128 v[128:131], v140
	ds_read_b128 v[132:135], v140 offset:1024
	ds_read_b128 v[136:139], v140 offset:2048
	ds_read_b128 v[140:143], v140 offset:3072
	ds_read_b128 v[144:147], v180
	ds_read_b128 v[148:151], v180 offset:1024
	ds_read_b128 v[152:155], v180 offset:2048
	ds_read_b128 v[180:183], v180 offset:3072
	v_lshl_add_u64 v[192:193], s[2:3], 0, v[176:177]
	s_add_i32 m0, s48, 0xc000
	ds_read_b128 v[184:187], v202
	ds_read_b128 v[188:191], v202 offset:1024
	ds_read_b128 v[204:207], v202 offset:2048
	ds_read_b128 v[208:211], v202 offset:3072
	ds_read_b128 v[212:215], v202 offset:4096
	ds_read_b128 v[216:219], v202 offset:5120
	ds_read_b128 v[220:223], v202 offset:6144
	ds_read_b128 v[224:227], v202 offset:7168
	global_load_lds_dwordx4 v[192:193], off
	v_lshl_add_u64 v[192:193], s[2:3], 0, v[178:179]
	s_add_i32 m0, s48, 0xe000
	s_nop 0
	global_load_lds_dwordx4 v[192:193], off
	s_waitcnt vmcnt(8)
	s_waitcnt lgkmcnt(0)
	s_barrier
	s_setprio 1
	v_mfma_f32_16x16x32_bf16 v[124:127], v[128:131], v[184:187], 0
	v_mfma_f32_16x16x32_bf16 v[120:123], v[136:139], v[184:187], 0
	v_mfma_f32_16x16x32_bf16 v[108:111], v[128:131], v[204:207], 0
	v_mfma_f32_16x16x32_bf16 v[104:107], v[136:139], v[204:207], 0
	v_mfma_f32_16x16x32_bf16 v[92:95], v[128:131], v[212:215], 0
	v_mfma_f32_16x16x32_bf16 v[88:91], v[136:139], v[212:215], 0
	v_mfma_f32_16x16x32_bf16 v[76:79], v[128:131], v[220:223], 0
	v_mfma_f32_16x16x32_bf16 v[72:75], v[136:139], v[220:223], 0
	v_mfma_f32_16x16x32_bf16 v[124:127], v[132:135], v[188:191], v[124:127]
	v_mfma_f32_16x16x32_bf16 v[120:123], v[140:143], v[188:191], v[120:123]
	v_mfma_f32_16x16x32_bf16 v[108:111], v[132:135], v[208:211], v[108:111]
	v_mfma_f32_16x16x32_bf16 v[104:107], v[140:143], v[208:211], v[104:107]
	v_mfma_f32_16x16x32_bf16 v[92:95], v[132:135], v[216:219], v[92:95]
	v_mfma_f32_16x16x32_bf16 v[88:91], v[140:143], v[216:219], v[88:91]
	v_mfma_f32_16x16x32_bf16 v[76:79], v[132:135], v[224:227], v[76:79]
	v_mfma_f32_16x16x32_bf16 v[72:75], v[140:143], v[224:227], v[72:75]
	s_setprio 0
	s_setprio 1
	v_mfma_f32_16x16x32_bf16 v[116:119], v[144:147], v[184:187], 0
	v_mfma_f32_16x16x32_bf16 v[112:115], v[152:155], v[184:187], 0
	v_mfma_f32_16x16x32_bf16 v[100:103], v[144:147], v[204:207], 0
	v_mfma_f32_16x16x32_bf16 v[96:99], v[152:155], v[204:207], 0
	v_mfma_f32_16x16x32_bf16 v[84:87], v[144:147], v[212:215], 0
	v_mfma_f32_16x16x32_bf16 v[80:83], v[152:155], v[212:215], 0
	v_mfma_f32_16x16x32_bf16 v[68:71], v[144:147], v[220:223], 0
	v_mfma_f32_16x16x32_bf16 v[64:67], v[152:155], v[220:223], 0
	v_mfma_f32_16x16x32_bf16 v[116:119], v[148:151], v[188:191], v[116:119]
	v_mfma_f32_16x16x32_bf16 v[112:115], v[180:183], v[188:191], v[112:115]
	v_mfma_f32_16x16x32_bf16 v[100:103], v[148:151], v[208:211], v[100:103]
	v_mfma_f32_16x16x32_bf16 v[96:99], v[180:183], v[208:211], v[96:99]
	v_mfma_f32_16x16x32_bf16 v[84:87], v[148:151], v[216:219], v[84:87]
	v_mfma_f32_16x16x32_bf16 v[80:83], v[180:183], v[216:219], v[80:83]
	v_mfma_f32_16x16x32_bf16 v[68:71], v[148:151], v[224:227], v[68:71]
	v_mfma_f32_16x16x32_bf16 v[64:67], v[180:183], v[224:227], v[64:67]
	s_setprio 0
	s_barrier
	s_add_i32 s63, s63, s47
	v_lshl_add_u64 v[192:193], s[88:89], 0, v[158:159]
	s_mov_b32 m0, s63
	ds_read_b128 v[184:187], v202 offset:16384
	ds_read_b128 v[188:191], v202 offset:17408
	ds_read_b128 v[204:207], v202 offset:18432
	ds_read_b128 v[208:211], v202 offset:19456
	ds_read_b128 v[212:215], v202 offset:20480
	ds_read_b128 v[216:219], v202 offset:21504
	ds_read_b128 v[220:223], v202 offset:22528
	ds_read_b128 v[224:227], v202 offset:23552
	global_load_lds_dwordx4 v[192:193], off
	s_add_i32 m0, s63, 0x2000
	v_lshl_add_u64 v[228:229], s[88:89], 0, v[168:169]
	s_add_u32 s88, s88, s8
	s_addc_u32 s89, s89, 0
	s_add_i32 s62, s62, s47
	global_load_lds_dwordx4 v[228:229], off
	v_lshl_add_u64 v[230:231], s[88:89], 0, v[158:159]
	s_mov_b32 m0, s62
	v_lshl_add_u64 v[232:233], s[88:89], 0, v[168:169]
	global_load_lds_dwordx4 v[230:231], off
	s_add_i32 m0, s62, 0x2000
	v_lshl_add_u64 v[234:235], s[34:35], 0, v[172:173]
	global_load_lds_dwordx4 v[232:233], off
	s_mov_b32 m0, s48
	v_lshl_add_u64 v[236:237], s[34:35], 0, v[170:171]
	global_load_lds_dwordx4 v[234:235], off
	s_mov_b32 m0, s49
	s_nop 0
	global_load_lds_dwordx4 v[236:237], off
	s_waitcnt vmcnt(8)
	s_waitcnt lgkmcnt(0)
	s_barrier
	s_setprio 1
	v_mfma_f32_16x16x32_bf16 v[60:63], v[128:131], v[184:187], 0
	v_mfma_f32_16x16x32_bf16 v[56:59], v[136:139], v[184:187], 0
	v_mfma_f32_16x16x32_bf16 v[44:47], v[128:131], v[204:207], 0
	v_mfma_f32_16x16x32_bf16 v[40:43], v[136:139], v[204:207], 0
	v_mfma_f32_16x16x32_bf16 v[28:31], v[128:131], v[212:215], 0
	v_mfma_f32_16x16x32_bf16 v[24:27], v[136:139], v[212:215], 0
	v_mfma_f32_16x16x32_bf16 v[12:15], v[128:131], v[220:223], 0
	v_mfma_f32_16x16x32_bf16 v[8:11], v[136:139], v[220:223], 0
	v_mfma_f32_16x16x32_bf16 v[60:63], v[132:135], v[188:191], v[60:63]
	v_mfma_f32_16x16x32_bf16 v[56:59], v[140:143], v[188:191], v[56:59]
	v_mfma_f32_16x16x32_bf16 v[44:47], v[132:135], v[208:211], v[44:47]
	v_mfma_f32_16x16x32_bf16 v[40:43], v[140:143], v[208:211], v[40:43]
	v_mfma_f32_16x16x32_bf16 v[28:31], v[132:135], v[216:219], v[28:31]
	v_mfma_f32_16x16x32_bf16 v[24:27], v[140:143], v[216:219], v[24:27]
	v_mfma_f32_16x16x32_bf16 v[12:15], v[132:135], v[224:227], v[12:15]
	v_mfma_f32_16x16x32_bf16 v[8:11], v[140:143], v[224:227], v[8:11]
	s_setprio 0
	s_setprio 1
	v_mfma_f32_16x16x32_bf16 v[52:55], v[144:147], v[184:187], 0
	v_mfma_f32_16x16x32_bf16 v[48:51], v[152:155], v[184:187], 0
	v_mfma_f32_16x16x32_bf16 v[36:39], v[144:147], v[204:207], 0
	v_mfma_f32_16x16x32_bf16 v[32:35], v[152:155], v[204:207], 0
	v_mfma_f32_16x16x32_bf16 v[20:23], v[144:147], v[212:215], 0
	v_mfma_f32_16x16x32_bf16 v[16:19], v[152:155], v[212:215], 0
	v_mfma_f32_16x16x32_bf16 v[4:7], v[144:147], v[220:223], 0
	v_mfma_f32_16x16x32_bf16 v[0:3], v[152:155], v[220:223], 0
	v_mfma_f32_16x16x32_bf16 v[52:55], v[148:151], v[188:191], v[52:55]
	v_mfma_f32_16x16x32_bf16 v[48:51], v[180:183], v[188:191], v[48:51]
	v_mfma_f32_16x16x32_bf16 v[36:39], v[148:151], v[208:211], v[36:39]
	v_mfma_f32_16x16x32_bf16 v[32:35], v[180:183], v[208:211], v[32:35]
	v_mfma_f32_16x16x32_bf16 v[20:23], v[148:151], v[216:219], v[20:23]
	v_mfma_f32_16x16x32_bf16 v[16:19], v[180:183], v[216:219], v[16:19]
	v_mfma_f32_16x16x32_bf16 v[4:7], v[148:151], v[224:227], v[4:7]
	v_mfma_f32_16x16x32_bf16 v[0:3], v[180:183], v[224:227], v[0:3]
	s_setprio 0
	s_barrier
	s_add_i32 s62, 0, 0x18000
	s_add_i32 s63, 0, 0x1c000
	v_add_u32_e32 v140, s62, v201
	v_add_u32_e32 v180, s63, v201
	ds_read_b128 v[128:131], v140
	ds_read_b128 v[132:135], v140 offset:1024
	ds_read_b128 v[136:139], v140 offset:2048
	ds_read_b128 v[140:143], v140 offset:3072
	ds_read_b128 v[144:147], v180
	ds_read_b128 v[148:151], v180 offset:1024
	ds_read_b128 v[152:155], v180 offset:2048
	ds_read_b128 v[180:183], v180 offset:3072
	s_add_u32 s34, s34, s8
	s_addc_u32 s35, s35, 0
	s_mov_b32 m0, s50
	v_lshl_add_u64 v[238:239], s[34:35], 0, v[172:173]
	ds_read_b128 v[184:187], v202 offset:32768
	ds_read_b128 v[188:191], v202 offset:33792
	ds_read_b128 v[204:207], v202 offset:34816
	ds_read_b128 v[208:211], v202 offset:35840
	ds_read_b128 v[212:215], v202 offset:36864
	ds_read_b128 v[216:219], v202 offset:37888
	ds_read_b128 v[220:223], v202 offset:38912
	ds_read_b128 v[224:227], v202 offset:39936
	global_load_lds_dwordx4 v[238:239], off
	v_lshl_add_u64 v[238:239], s[34:35], 0, v[170:171]
	s_mov_b32 m0, s51
	s_nop 0
	global_load_lds_dwordx4 v[238:239], off
	s_waitcnt vmcnt(8)
	s_waitcnt lgkmcnt(0)
	s_barrier
	s_setprio 1
	v_mfma_f32_16x16x32_bf16 v[124:127], v[128:131], v[184:187], v[124:127]
	v_mfma_f32_16x16x32_bf16 v[120:123], v[136:139], v[184:187], v[120:123]
	v_mfma_f32_16x16x32_bf16 v[108:111], v[128:131], v[204:207], v[108:111]
	v_mfma_f32_16x16x32_bf16 v[104:107], v[136:139], v[204:207], v[104:107]
	v_mfma_f32_16x16x32_bf16 v[92:95], v[128:131], v[212:215], v[92:95]
	v_mfma_f32_16x16x32_bf16 v[88:91], v[136:139], v[212:215], v[88:91]
	v_mfma_f32_16x16x32_bf16 v[76:79], v[128:131], v[220:223], v[76:79]
	v_mfma_f32_16x16x32_bf16 v[72:75], v[136:139], v[220:223], v[72:75]
	v_mfma_f32_16x16x32_bf16 v[124:127], v[132:135], v[188:191], v[124:127]
	v_mfma_f32_16x16x32_bf16 v[120:123], v[140:143], v[188:191], v[120:123]
	v_mfma_f32_16x16x32_bf16 v[108:111], v[132:135], v[208:211], v[108:111]
	v_mfma_f32_16x16x32_bf16 v[104:107], v[140:143], v[208:211], v[104:107]
	v_mfma_f32_16x16x32_bf16 v[92:95], v[132:135], v[216:219], v[92:95]
	v_mfma_f32_16x16x32_bf16 v[88:91], v[140:143], v[216:219], v[88:91]
	v_mfma_f32_16x16x32_bf16 v[76:79], v[132:135], v[224:227], v[76:79]
	v_mfma_f32_16x16x32_bf16 v[72:75], v[140:143], v[224:227], v[72:75]
	s_setprio 0
	s_setprio 1
	v_mfma_f32_16x16x32_bf16 v[116:119], v[144:147], v[184:187], v[116:119]
	v_mfma_f32_16x16x32_bf16 v[112:115], v[152:155], v[184:187], v[112:115]
	v_mfma_f32_16x16x32_bf16 v[100:103], v[144:147], v[204:207], v[100:103]
	v_mfma_f32_16x16x32_bf16 v[96:99], v[152:155], v[204:207], v[96:99]
	v_mfma_f32_16x16x32_bf16 v[84:87], v[144:147], v[212:215], v[84:87]
	v_mfma_f32_16x16x32_bf16 v[80:83], v[152:155], v[212:215], v[80:83]
	v_mfma_f32_16x16x32_bf16 v[68:71], v[144:147], v[220:223], v[68:71]
	v_mfma_f32_16x16x32_bf16 v[64:67], v[152:155], v[220:223], v[64:67]
	v_mfma_f32_16x16x32_bf16 v[116:119], v[148:151], v[188:191], v[116:119]
	v_mfma_f32_16x16x32_bf16 v[112:115], v[180:183], v[188:191], v[112:115]
	v_mfma_f32_16x16x32_bf16 v[100:103], v[148:151], v[208:211], v[100:103]
	v_mfma_f32_16x16x32_bf16 v[96:99], v[180:183], v[208:211], v[96:99]
	v_mfma_f32_16x16x32_bf16 v[84:87], v[148:151], v[216:219], v[84:87]
	v_mfma_f32_16x16x32_bf16 v[80:83], v[180:183], v[216:219], v[80:83]
	v_mfma_f32_16x16x32_bf16 v[68:71], v[148:151], v[224:227], v[68:71]
	v_mfma_f32_16x16x32_bf16 v[64:67], v[180:183], v[224:227], v[64:67]
	s_setprio 0
	s_barrier
	s_add_i32 s34, s62, s47
	v_lshl_add_u64 v[192:193], v[192:193], 0, s[14:15]
	s_mov_b32 m0, s34
	ds_read_b128 v[184:187], v202 offset:49152
	ds_read_b128 v[188:191], v202 offset:50176
	ds_read_b128 v[204:207], v202 offset:51200
	ds_read_b128 v[208:211], v202 offset:52224
	ds_read_b128 v[212:215], v202 offset:53248
	ds_read_b128 v[216:219], v202 offset:54272
	ds_read_b128 v[220:223], v202 offset:55296
	ds_read_b128 v[224:227], v202 offset:56320
	global_load_lds_dwordx4 v[192:193], off
	v_lshl_add_u64 v[192:193], v[228:229], 0, s[14:15]
	s_add_i32 m0, s34, 0x2000
	s_add_i32 s34, s63, s47
	global_load_lds_dwordx4 v[192:193], off
	v_lshl_add_u64 v[192:193], v[230:231], 0, s[14:15]
	s_mov_b32 m0, s34
	s_nop 0
	global_load_lds_dwordx4 v[192:193], off
	v_lshl_add_u64 v[192:193], v[232:233], 0, s[14:15]
	s_add_i32 m0, s34, 0x2000
	s_nop 0
	global_load_lds_dwordx4 v[192:193], off
	v_lshl_add_u64 v[192:193], v[234:235], 0, s[14:15]
	s_mov_b32 m0, s60
	s_nop 0
	global_load_lds_dwordx4 v[192:193], off
	v_lshl_add_u64 v[192:193], v[236:237], 0, s[14:15]
	s_mov_b32 m0, s61
	s_nop 0
	global_load_lds_dwordx4 v[192:193], off
	s_waitcnt vmcnt(8)
	s_waitcnt lgkmcnt(0)
	s_barrier
	s_setprio 1
	v_mfma_f32_16x16x32_bf16 v[60:63], v[128:131], v[184:187], v[60:63]
	v_mfma_f32_16x16x32_bf16 v[56:59], v[136:139], v[184:187], v[56:59]
	v_mfma_f32_16x16x32_bf16 v[44:47], v[128:131], v[204:207], v[44:47]
	v_mfma_f32_16x16x32_bf16 v[40:43], v[136:139], v[204:207], v[40:43]
	v_mfma_f32_16x16x32_bf16 v[28:31], v[128:131], v[212:215], v[28:31]
	v_mfma_f32_16x16x32_bf16 v[24:27], v[136:139], v[212:215], v[24:27]
	v_mfma_f32_16x16x32_bf16 v[12:15], v[128:131], v[220:223], v[12:15]
	v_mfma_f32_16x16x32_bf16 v[8:11], v[136:139], v[220:223], v[8:11]
	v_mfma_f32_16x16x32_bf16 v[60:63], v[132:135], v[188:191], v[60:63]
	v_mfma_f32_16x16x32_bf16 v[56:59], v[140:143], v[188:191], v[56:59]
	v_mfma_f32_16x16x32_bf16 v[44:47], v[132:135], v[208:211], v[44:47]
	v_mfma_f32_16x16x32_bf16 v[40:43], v[140:143], v[208:211], v[40:43]
	v_mfma_f32_16x16x32_bf16 v[28:31], v[132:135], v[216:219], v[28:31]
	v_mfma_f32_16x16x32_bf16 v[24:27], v[140:143], v[216:219], v[24:27]
	v_mfma_f32_16x16x32_bf16 v[12:15], v[132:135], v[224:227], v[12:15]
	v_mfma_f32_16x16x32_bf16 v[8:11], v[140:143], v[224:227], v[8:11]
	s_setprio 0
	s_setprio 1
	v_mfma_f32_16x16x32_bf16 v[52:55], v[144:147], v[184:187], v[52:55]
	v_mfma_f32_16x16x32_bf16 v[48:51], v[152:155], v[184:187], v[48:51]
	v_mfma_f32_16x16x32_bf16 v[36:39], v[144:147], v[204:207], v[36:39]
	v_mfma_f32_16x16x32_bf16 v[32:35], v[152:155], v[204:207], v[32:35]
	v_mfma_f32_16x16x32_bf16 v[20:23], v[144:147], v[212:215], v[20:23]
	v_mfma_f32_16x16x32_bf16 v[16:19], v[152:155], v[212:215], v[16:19]
	v_mfma_f32_16x16x32_bf16 v[4:7], v[144:147], v[220:223], v[4:7]
	v_mfma_f32_16x16x32_bf16 v[0:3], v[152:155], v[220:223], v[0:3]
	v_mfma_f32_16x16x32_bf16 v[52:55], v[148:151], v[188:191], v[52:55]
	v_mfma_f32_16x16x32_bf16 v[48:51], v[180:183], v[188:191], v[48:51]
	v_mfma_f32_16x16x32_bf16 v[36:39], v[148:151], v[208:211], v[36:39]
	v_mfma_f32_16x16x32_bf16 v[32:35], v[180:183], v[208:211], v[32:35]
	v_mfma_f32_16x16x32_bf16 v[20:23], v[148:151], v[216:219], v[20:23]
	v_mfma_f32_16x16x32_bf16 v[16:19], v[180:183], v[216:219], v[16:19]
	v_mfma_f32_16x16x32_bf16 v[4:7], v[148:151], v[224:227], v[4:7]
	v_mfma_f32_16x16x32_bf16 v[0:3], v[180:183], v[224:227], v[0:3]
	s_setprio 0
	s_barrier
	s_add_u32 s2, s2, 0x100
	s_addc_u32 s3, s3, 0
	s_add_u32 s40, s40, 0x100
	s_addc_u32 s41, s41, 0
	s_mov_b32 s34, s86
.LBB0_497:
	s_add_i32 s86, s34, 2
	s_add_u32 s62, s2, 0x80
	s_addc_u32 s35, s3, 0
	s_add_i32 s63, 0, 0x10000
	s_cmp_eq_u32 s80, s34
	s_cselect_b32 s35, s17, s35
	s_cselect_b32 s34, s16, s62
	s_cselect_b32 s89, s25, s41
	s_cselect_b32 s88, s24, s40
	s_add_i32 s62, 0, 0x14000
	v_add_u32_e32 v140, s63, v201
	v_add_u32_e32 v180, s62, v201
	ds_read_b128 v[128:131], v140
	ds_read_b128 v[132:135], v140 offset:1024
	ds_read_b128 v[136:139], v140 offset:2048
	ds_read_b128 v[140:143], v140 offset:3072
	ds_read_b128 v[144:147], v180
	ds_read_b128 v[148:151], v180 offset:1024
	ds_read_b128 v[152:155], v180 offset:2048
	ds_read_b128 v[180:183], v180 offset:3072
	v_lshl_add_u64 v[192:193], s[2:3], 0, v[176:177]
	s_add_i32 m0, s48, 0xc000
	ds_read_b128 v[184:187], v202
	ds_read_b128 v[188:191], v202 offset:1024
	ds_read_b128 v[204:207], v202 offset:2048
	ds_read_b128 v[208:211], v202 offset:3072
	ds_read_b128 v[212:215], v202 offset:4096
	ds_read_b128 v[216:219], v202 offset:5120
	ds_read_b128 v[220:223], v202 offset:6144
	ds_read_b128 v[224:227], v202 offset:7168
	global_load_lds_dwordx4 v[192:193], off
	v_lshl_add_u64 v[192:193], s[2:3], 0, v[178:179]
	s_add_i32 m0, s48, 0xe000
	s_nop 0
	global_load_lds_dwordx4 v[192:193], off
	s_waitcnt vmcnt(8)
	s_waitcnt lgkmcnt(0)
	s_barrier
	s_setprio 1
	v_mfma_f32_16x16x32_bf16 v[124:127], v[128:131], v[184:187], v[124:127]
	v_mfma_f32_16x16x32_bf16 v[120:123], v[136:139], v[184:187], v[120:123]
	v_mfma_f32_16x16x32_bf16 v[108:111], v[128:131], v[204:207], v[108:111]
	v_mfma_f32_16x16x32_bf16 v[104:107], v[136:139], v[204:207], v[104:107]
	v_mfma_f32_16x16x32_bf16 v[92:95], v[128:131], v[212:215], v[92:95]
	v_mfma_f32_16x16x32_bf16 v[88:91], v[136:139], v[212:215], v[88:91]
	v_mfma_f32_16x16x32_bf16 v[76:79], v[128:131], v[220:223], v[76:79]
	v_mfma_f32_16x16x32_bf16 v[72:75], v[136:139], v[220:223], v[72:75]
	v_mfma_f32_16x16x32_bf16 v[124:127], v[132:135], v[188:191], v[124:127]
	v_mfma_f32_16x16x32_bf16 v[120:123], v[140:143], v[188:191], v[120:123]
	v_mfma_f32_16x16x32_bf16 v[108:111], v[132:135], v[208:211], v[108:111]
	v_mfma_f32_16x16x32_bf16 v[104:107], v[140:143], v[208:211], v[104:107]
	v_mfma_f32_16x16x32_bf16 v[92:95], v[132:135], v[216:219], v[92:95]
	v_mfma_f32_16x16x32_bf16 v[88:91], v[140:143], v[216:219], v[88:91]
	v_mfma_f32_16x16x32_bf16 v[76:79], v[132:135], v[224:227], v[76:79]
	v_mfma_f32_16x16x32_bf16 v[72:75], v[140:143], v[224:227], v[72:75]
	s_setprio 0
	s_setprio 1
	v_mfma_f32_16x16x32_bf16 v[116:119], v[144:147], v[184:187], v[116:119]
	v_mfma_f32_16x16x32_bf16 v[112:115], v[152:155], v[184:187], v[112:115]
	v_mfma_f32_16x16x32_bf16 v[100:103], v[144:147], v[204:207], v[100:103]
	v_mfma_f32_16x16x32_bf16 v[96:99], v[152:155], v[204:207], v[96:99]
	v_mfma_f32_16x16x32_bf16 v[84:87], v[144:147], v[212:215], v[84:87]
	v_mfma_f32_16x16x32_bf16 v[80:83], v[152:155], v[212:215], v[80:83]
	v_mfma_f32_16x16x32_bf16 v[68:71], v[144:147], v[220:223], v[68:71]
	v_mfma_f32_16x16x32_bf16 v[64:67], v[152:155], v[220:223], v[64:67]
	v_mfma_f32_16x16x32_bf16 v[116:119], v[148:151], v[188:191], v[116:119]
	v_mfma_f32_16x16x32_bf16 v[112:115], v[180:183], v[188:191], v[112:115]
	v_mfma_f32_16x16x32_bf16 v[100:103], v[148:151], v[208:211], v[100:103]
	v_mfma_f32_16x16x32_bf16 v[96:99], v[180:183], v[208:211], v[96:99]
	v_mfma_f32_16x16x32_bf16 v[84:87], v[148:151], v[216:219], v[84:87]
	v_mfma_f32_16x16x32_bf16 v[80:83], v[180:183], v[216:219], v[80:83]
	v_mfma_f32_16x16x32_bf16 v[68:71], v[148:151], v[224:227], v[68:71]
	v_mfma_f32_16x16x32_bf16 v[64:67], v[180:183], v[224:227], v[64:67]
	s_setprio 0
	s_barrier
	s_add_i32 s63, s63, s47
	v_lshl_add_u64 v[192:193], s[88:89], 0, v[158:159]
	s_mov_b32 m0, s63
	ds_read_b128 v[184:187], v202 offset:16384
	ds_read_b128 v[188:191], v202 offset:17408
	ds_read_b128 v[204:207], v202 offset:18432
	ds_read_b128 v[208:211], v202 offset:19456
	ds_read_b128 v[212:215], v202 offset:20480
	ds_read_b128 v[216:219], v202 offset:21504
	ds_read_b128 v[220:223], v202 offset:22528
	ds_read_b128 v[224:227], v202 offset:23552
	global_load_lds_dwordx4 v[192:193], off
	s_add_i32 m0, s63, 0x2000
	v_lshl_add_u64 v[228:229], s[88:89], 0, v[168:169]
	s_add_u32 s88, s88, s8
	s_addc_u32 s89, s89, 0
	s_add_i32 s62, s62, s47
	global_load_lds_dwordx4 v[228:229], off
	v_lshl_add_u64 v[230:231], s[88:89], 0, v[158:159]
	s_mov_b32 m0, s62
	v_lshl_add_u64 v[232:233], s[88:89], 0, v[168:169]
	global_load_lds_dwordx4 v[230:231], off
	s_add_i32 m0, s62, 0x2000
	v_lshl_add_u64 v[234:235], s[34:35], 0, v[172:173]
	global_load_lds_dwordx4 v[232:233], off
	s_mov_b32 m0, s48
	v_lshl_add_u64 v[236:237], s[34:35], 0, v[170:171]
	global_load_lds_dwordx4 v[234:235], off
	s_mov_b32 m0, s49
	s_nop 0
	global_load_lds_dwordx4 v[236:237], off
	s_waitcnt vmcnt(8)
	s_waitcnt lgkmcnt(0)
	s_barrier
	s_setprio 1
	v_mfma_f32_16x16x32_bf16 v[60:63], v[128:131], v[184:187], v[60:63]
	v_mfma_f32_16x16x32_bf16 v[56:59], v[136:139], v[184:187], v[56:59]
	v_mfma_f32_16x16x32_bf16 v[44:47], v[128:131], v[204:207], v[44:47]
	v_mfma_f32_16x16x32_bf16 v[40:43], v[136:139], v[204:207], v[40:43]
	v_mfma_f32_16x16x32_bf16 v[28:31], v[128:131], v[212:215], v[28:31]
	v_mfma_f32_16x16x32_bf16 v[24:27], v[136:139], v[212:215], v[24:27]
	v_mfma_f32_16x16x32_bf16 v[12:15], v[128:131], v[220:223], v[12:15]
	v_mfma_f32_16x16x32_bf16 v[8:11], v[136:139], v[220:223], v[8:11]
	v_mfma_f32_16x16x32_bf16 v[60:63], v[132:135], v[188:191], v[60:63]
	v_mfma_f32_16x16x32_bf16 v[56:59], v[140:143], v[188:191], v[56:59]
	v_mfma_f32_16x16x32_bf16 v[44:47], v[132:135], v[208:211], v[44:47]
	v_mfma_f32_16x16x32_bf16 v[40:43], v[140:143], v[208:211], v[40:43]
	v_mfma_f32_16x16x32_bf16 v[28:31], v[132:135], v[216:219], v[28:31]
	v_mfma_f32_16x16x32_bf16 v[24:27], v[140:143], v[216:219], v[24:27]
	v_mfma_f32_16x16x32_bf16 v[12:15], v[132:135], v[224:227], v[12:15]
	v_mfma_f32_16x16x32_bf16 v[8:11], v[140:143], v[224:227], v[8:11]
	s_setprio 0
	s_setprio 1
	v_mfma_f32_16x16x32_bf16 v[52:55], v[144:147], v[184:187], v[52:55]
	v_mfma_f32_16x16x32_bf16 v[48:51], v[152:155], v[184:187], v[48:51]
	v_mfma_f32_16x16x32_bf16 v[36:39], v[144:147], v[204:207], v[36:39]
	v_mfma_f32_16x16x32_bf16 v[32:35], v[152:155], v[204:207], v[32:35]
	v_mfma_f32_16x16x32_bf16 v[20:23], v[144:147], v[212:215], v[20:23]
	v_mfma_f32_16x16x32_bf16 v[16:19], v[152:155], v[212:215], v[16:19]
	v_mfma_f32_16x16x32_bf16 v[4:7], v[144:147], v[220:223], v[4:7]
	v_mfma_f32_16x16x32_bf16 v[0:3], v[152:155], v[220:223], v[0:3]
	v_mfma_f32_16x16x32_bf16 v[52:55], v[148:151], v[188:191], v[52:55]
	v_mfma_f32_16x16x32_bf16 v[48:51], v[180:183], v[188:191], v[48:51]
	v_mfma_f32_16x16x32_bf16 v[36:39], v[148:151], v[208:211], v[36:39]
	v_mfma_f32_16x16x32_bf16 v[32:35], v[180:183], v[208:211], v[32:35]
	v_mfma_f32_16x16x32_bf16 v[20:23], v[148:151], v[216:219], v[20:23]
	v_mfma_f32_16x16x32_bf16 v[16:19], v[180:183], v[216:219], v[16:19]
	v_mfma_f32_16x16x32_bf16 v[4:7], v[148:151], v[224:227], v[4:7]
	v_mfma_f32_16x16x32_bf16 v[0:3], v[180:183], v[224:227], v[0:3]
	s_setprio 0
	s_barrier
	s_add_i32 s62, 0, 0x18000
	s_add_i32 s63, 0, 0x1c000
	v_add_u32_e32 v140, s62, v201
	v_add_u32_e32 v180, s63, v201
	ds_read_b128 v[128:131], v140
	ds_read_b128 v[132:135], v140 offset:1024
	ds_read_b128 v[136:139], v140 offset:2048
	ds_read_b128 v[140:143], v140 offset:3072
	ds_read_b128 v[144:147], v180
	ds_read_b128 v[148:151], v180 offset:1024
	ds_read_b128 v[152:155], v180 offset:2048
	ds_read_b128 v[180:183], v180 offset:3072
	s_add_u32 s34, s34, s8
	s_addc_u32 s35, s35, 0
	s_mov_b32 m0, s50
	v_lshl_add_u64 v[238:239], s[34:35], 0, v[172:173]
	ds_read_b128 v[184:187], v202 offset:32768
	ds_read_b128 v[188:191], v202 offset:33792
	ds_read_b128 v[204:207], v202 offset:34816
	ds_read_b128 v[208:211], v202 offset:35840
	ds_read_b128 v[212:215], v202 offset:36864
	ds_read_b128 v[216:219], v202 offset:37888
	ds_read_b128 v[220:223], v202 offset:38912
	ds_read_b128 v[224:227], v202 offset:39936
	global_load_lds_dwordx4 v[238:239], off
	v_lshl_add_u64 v[238:239], s[34:35], 0, v[170:171]
	s_mov_b32 m0, s51
	s_nop 0
	global_load_lds_dwordx4 v[238:239], off
	s_waitcnt vmcnt(8)
	s_waitcnt lgkmcnt(0)
	s_barrier
	s_setprio 1
	v_mfma_f32_16x16x32_bf16 v[124:127], v[128:131], v[184:187], v[124:127]
	v_mfma_f32_16x16x32_bf16 v[120:123], v[136:139], v[184:187], v[120:123]
	v_mfma_f32_16x16x32_bf16 v[108:111], v[128:131], v[204:207], v[108:111]
	v_mfma_f32_16x16x32_bf16 v[104:107], v[136:139], v[204:207], v[104:107]
	v_mfma_f32_16x16x32_bf16 v[92:95], v[128:131], v[212:215], v[92:95]
	v_mfma_f32_16x16x32_bf16 v[88:91], v[136:139], v[212:215], v[88:91]
	v_mfma_f32_16x16x32_bf16 v[76:79], v[128:131], v[220:223], v[76:79]
	v_mfma_f32_16x16x32_bf16 v[72:75], v[136:139], v[220:223], v[72:75]
	v_mfma_f32_16x16x32_bf16 v[124:127], v[132:135], v[188:191], v[124:127]
	v_mfma_f32_16x16x32_bf16 v[120:123], v[140:143], v[188:191], v[120:123]
	v_mfma_f32_16x16x32_bf16 v[108:111], v[132:135], v[208:211], v[108:111]
	v_mfma_f32_16x16x32_bf16 v[104:107], v[140:143], v[208:211], v[104:107]
	v_mfma_f32_16x16x32_bf16 v[92:95], v[132:135], v[216:219], v[92:95]
	v_mfma_f32_16x16x32_bf16 v[88:91], v[140:143], v[216:219], v[88:91]
	v_mfma_f32_16x16x32_bf16 v[76:79], v[132:135], v[224:227], v[76:79]
	v_mfma_f32_16x16x32_bf16 v[72:75], v[140:143], v[224:227], v[72:75]
	s_setprio 0
	s_setprio 1
	v_mfma_f32_16x16x32_bf16 v[116:119], v[144:147], v[184:187], v[116:119]
	v_mfma_f32_16x16x32_bf16 v[112:115], v[152:155], v[184:187], v[112:115]
	v_mfma_f32_16x16x32_bf16 v[100:103], v[144:147], v[204:207], v[100:103]
	v_mfma_f32_16x16x32_bf16 v[96:99], v[152:155], v[204:207], v[96:99]
	v_mfma_f32_16x16x32_bf16 v[84:87], v[144:147], v[212:215], v[84:87]
	v_mfma_f32_16x16x32_bf16 v[80:83], v[152:155], v[212:215], v[80:83]
	v_mfma_f32_16x16x32_bf16 v[68:71], v[144:147], v[220:223], v[68:71]
	v_mfma_f32_16x16x32_bf16 v[64:67], v[152:155], v[220:223], v[64:67]
	v_mfma_f32_16x16x32_bf16 v[116:119], v[148:151], v[188:191], v[116:119]
	v_mfma_f32_16x16x32_bf16 v[112:115], v[180:183], v[188:191], v[112:115]
	v_mfma_f32_16x16x32_bf16 v[100:103], v[148:151], v[208:211], v[100:103]
	v_mfma_f32_16x16x32_bf16 v[96:99], v[180:183], v[208:211], v[96:99]
	v_mfma_f32_16x16x32_bf16 v[84:87], v[148:151], v[216:219], v[84:87]
	v_mfma_f32_16x16x32_bf16 v[80:83], v[180:183], v[216:219], v[80:83]
	v_mfma_f32_16x16x32_bf16 v[68:71], v[148:151], v[224:227], v[68:71]
	v_mfma_f32_16x16x32_bf16 v[64:67], v[180:183], v[224:227], v[64:67]
	s_setprio 0
	s_barrier
	s_add_i32 s34, s62, s47
	v_lshl_add_u64 v[192:193], v[192:193], 0, s[14:15]
	s_mov_b32 m0, s34
	ds_read_b128 v[184:187], v202 offset:49152
	ds_read_b128 v[188:191], v202 offset:50176
	ds_read_b128 v[204:207], v202 offset:51200
	ds_read_b128 v[208:211], v202 offset:52224
	ds_read_b128 v[212:215], v202 offset:53248
	ds_read_b128 v[216:219], v202 offset:54272
	ds_read_b128 v[220:223], v202 offset:55296
	ds_read_b128 v[224:227], v202 offset:56320
	global_load_lds_dwordx4 v[192:193], off
	v_lshl_add_u64 v[192:193], v[228:229], 0, s[14:15]
	s_add_i32 m0, s34, 0x2000
	s_add_i32 s34, s63, s47
	global_load_lds_dwordx4 v[192:193], off
	v_lshl_add_u64 v[192:193], v[230:231], 0, s[14:15]
	s_mov_b32 m0, s34
	s_nop 0
	global_load_lds_dwordx4 v[192:193], off
	v_lshl_add_u64 v[192:193], v[232:233], 0, s[14:15]
	s_add_i32 m0, s34, 0x2000
	s_nop 0
	global_load_lds_dwordx4 v[192:193], off
	v_lshl_add_u64 v[192:193], v[234:235], 0, s[14:15]
	s_mov_b32 m0, s60
	s_nop 0
	global_load_lds_dwordx4 v[192:193], off
	v_lshl_add_u64 v[192:193], v[236:237], 0, s[14:15]
	s_mov_b32 m0, s61
	s_nop 0
	global_load_lds_dwordx4 v[192:193], off
	s_waitcnt vmcnt(8)
	s_waitcnt lgkmcnt(0)
	s_barrier
	s_setprio 1
	v_mfma_f32_16x16x32_bf16 v[60:63], v[128:131], v[184:187], v[60:63]
	v_mfma_f32_16x16x32_bf16 v[56:59], v[136:139], v[184:187], v[56:59]
	v_mfma_f32_16x16x32_bf16 v[44:47], v[128:131], v[204:207], v[44:47]
	v_mfma_f32_16x16x32_bf16 v[40:43], v[136:139], v[204:207], v[40:43]
	v_mfma_f32_16x16x32_bf16 v[28:31], v[128:131], v[212:215], v[28:31]
	v_mfma_f32_16x16x32_bf16 v[24:27], v[136:139], v[212:215], v[24:27]
	v_mfma_f32_16x16x32_bf16 v[12:15], v[128:131], v[220:223], v[12:15]
	v_mfma_f32_16x16x32_bf16 v[8:11], v[136:139], v[220:223], v[8:11]
	v_mfma_f32_16x16x32_bf16 v[60:63], v[132:135], v[188:191], v[60:63]
	v_mfma_f32_16x16x32_bf16 v[56:59], v[140:143], v[188:191], v[56:59]
	v_mfma_f32_16x16x32_bf16 v[44:47], v[132:135], v[208:211], v[44:47]
	v_mfma_f32_16x16x32_bf16 v[40:43], v[140:143], v[208:211], v[40:43]
	v_mfma_f32_16x16x32_bf16 v[28:31], v[132:135], v[216:219], v[28:31]
	v_mfma_f32_16x16x32_bf16 v[24:27], v[140:143], v[216:219], v[24:27]
	v_mfma_f32_16x16x32_bf16 v[12:15], v[132:135], v[224:227], v[12:15]
	v_mfma_f32_16x16x32_bf16 v[8:11], v[140:143], v[224:227], v[8:11]
	s_setprio 0
	s_setprio 1
	v_mfma_f32_16x16x32_bf16 v[52:55], v[144:147], v[184:187], v[52:55]
	v_mfma_f32_16x16x32_bf16 v[48:51], v[152:155], v[184:187], v[48:51]
	v_mfma_f32_16x16x32_bf16 v[36:39], v[144:147], v[204:207], v[36:39]
	v_mfma_f32_16x16x32_bf16 v[32:35], v[152:155], v[204:207], v[32:35]
	v_mfma_f32_16x16x32_bf16 v[20:23], v[144:147], v[212:215], v[20:23]
	v_mfma_f32_16x16x32_bf16 v[16:19], v[152:155], v[212:215], v[16:19]
	v_mfma_f32_16x16x32_bf16 v[4:7], v[144:147], v[220:223], v[4:7]
	v_mfma_f32_16x16x32_bf16 v[0:3], v[152:155], v[220:223], v[0:3]
	v_mfma_f32_16x16x32_bf16 v[52:55], v[148:151], v[188:191], v[52:55]
	v_mfma_f32_16x16x32_bf16 v[48:51], v[180:183], v[188:191], v[48:51]
	v_mfma_f32_16x16x32_bf16 v[36:39], v[148:151], v[208:211], v[36:39]
	v_mfma_f32_16x16x32_bf16 v[32:35], v[180:183], v[208:211], v[32:35]
	v_mfma_f32_16x16x32_bf16 v[20:23], v[148:151], v[216:219], v[20:23]
	v_mfma_f32_16x16x32_bf16 v[16:19], v[180:183], v[216:219], v[16:19]
	v_mfma_f32_16x16x32_bf16 v[4:7], v[148:151], v[224:227], v[4:7]
	v_mfma_f32_16x16x32_bf16 v[0:3], v[180:183], v[224:227], v[0:3]
	s_setprio 0
	s_barrier
	s_add_u32 s2, s2, 0x100
	s_addc_u32 s3, s3, 0
	s_add_u32 s40, s40, 0x100
	s_addc_u32 s41, s41, 0
	s_cmp_ge_u32 s86, s64
	s_mov_b32 s34, s86
	s_cbranch_scc0 .LBB0_497
	s_and_b64 vcc, exec, s[12:13]
	s_cbranch_vccz .LBB0_500
	s_barrier

.LBB0_628:
	s_ashr_i32 s13, s12, 31
	s_lshl_b64 s[6:7], s[12:13], 19
	s_add_u32 s6, s30, s6
	s_addc_u32 s7, s31, s7
	s_and_b64 s[24:25], s[38:39], exec
	s_cselect_b32 s13, s7, s35
	s_cselect_b32 s29, s6, s34
	s_ashr_i32 s5, s4, 31
	s_lshl_b64 s[24:25], s[4:5], 19
	s_add_u32 s24, s49, s24
	s_addc_u32 s25, s50, s25
	s_and_b64 s[42:43], s[38:39], exec
	s_cselect_b32 s5, s25, s41
	s_cselect_b32 s82, s24, s40
	s_add_u32 s34, s34, 0x40080
	s_addc_u32 s35, s35, 0
	s_add_u32 s83, s40, 0x100
	s_addc_u32 s84, s41, 0
	s_mov_b32 s85, -2
	s_add_u32 s40, s34, 0xfffc0080
	s_addc_u32 s41, s35, -1
	s_add_i32 s62, 0, 0x10000
	s_cmp_eq_u32 s85, 12
	s_cselect_b32 s43, s13, s41
	s_cselect_b32 s42, s29, s40
	s_cselect_b32 s41, s5, s84
	s_cselect_b32 s40, s82, s83
	s_add_i32 s63, 0, 0x14000
	s_add_u32 s86, s34, 0xfffc0000
	s_addc_u32 s87, s35, -1
	s_mov_b32 m0, s76
	v_add_u32_e32 v152, s62, v172
	v_add_u32_e32 v158, s63, v172
	v_add_u32_e32 v245, s62, v243
	v_add_u32_e32 v246, s63, v243
	global_load_lds_dwordx4 v132, s[86:87]
	s_mov_b32 m0, s77
	ds_read_b128 v[128:131], v152
	global_load_lds_dwordx4 v136, s[86:87]
	ds_read_b128 v[144:147], v245
	ds_read_b128 v[148:151], v152 offset:2048
	ds_read_b128 v[152:155], v245 offset:2048
	ds_read_b128 v[174:177], v158
	ds_read_b128 v[178:181], v246
	ds_read_b128 v[182:185], v158 offset:2048
	ds_read_b128 v[186:189], v246 offset:2048
	ds_read_b128 v[190:193], v173
	ds_read_b128 v[198:201], v244
	ds_read_b128 v[202:205], v173 offset:2048
	ds_read_b128 v[206:209], v244 offset:2048
	ds_read_b128 v[210:213], v173 offset:4096
	ds_read_b128 v[214:217], v244 offset:4096
	ds_read_b128 v[218:221], v173 offset:6144
	ds_read_b128 v[222:225], v244 offset:6144
	s_waitcnt vmcnt(6)
	s_waitcnt lgkmcnt(0)
	s_barrier
	s_setprio 1
	v_mfma_f32_16x16x32_bf16 v[124:127], v[128:131], v[190:193], 0
	v_mfma_f32_16x16x32_bf16 v[116:119], v[148:151], v[190:193], 0
	v_mfma_f32_16x16x32_bf16 v[108:111], v[128:131], v[202:205], 0
	s_add_i32 m0, s51, 0xc000
	v_mfma_f32_16x16x32_bf16 v[100:103], v[148:151], v[202:205], 0
	v_mfma_f32_16x16x32_bf16 v[92:95], v[128:131], v[210:213], 0
	global_load_lds_dwordx4 v132, s[34:35]
	v_mfma_f32_16x16x32_bf16 v[84:87], v[148:151], v[210:213], 0
	v_mfma_f32_16x16x32_bf16 v[76:79], v[128:131], v[218:221], 0
	v_mfma_f32_16x16x32_bf16 v[68:71], v[148:151], v[218:221], 0
	v_mfma_f32_16x16x32_bf16 v[124:127], v[144:147], v[198:201], v[124:127]
	v_mfma_f32_16x16x32_bf16 v[116:119], v[152:155], v[198:201], v[116:119]
	v_mfma_f32_16x16x32_bf16 v[108:111], v[144:147], v[206:209], v[108:111]
	s_add_i32 m0, s51, 0xe000
	v_mfma_f32_16x16x32_bf16 v[100:103], v[152:155], v[206:209], v[100:103]
	v_mfma_f32_16x16x32_bf16 v[92:95], v[144:147], v[214:217], v[92:95]
	global_load_lds_dwordx4 v136, s[34:35]
	v_mfma_f32_16x16x32_bf16 v[84:87], v[152:155], v[214:217], v[84:87]
	v_mfma_f32_16x16x32_bf16 v[76:79], v[144:147], v[222:225], v[76:79]
	v_mfma_f32_16x16x32_bf16 v[68:71], v[152:155], v[222:225], v[68:71]
	s_setprio 0
	s_setprio 1
	v_mfma_f32_16x16x32_bf16 v[120:123], v[174:177], v[190:193], 0
	v_mfma_f32_16x16x32_bf16 v[112:115], v[182:185], v[190:193], 0
	v_mfma_f32_16x16x32_bf16 v[104:107], v[174:177], v[202:205], 0
	v_mfma_f32_16x16x32_bf16 v[96:99], v[182:185], v[202:205], 0
	v_mfma_f32_16x16x32_bf16 v[88:91], v[174:177], v[210:213], 0
	v_mfma_f32_16x16x32_bf16 v[80:83], v[182:185], v[210:213], 0
	v_mfma_f32_16x16x32_bf16 v[72:75], v[174:177], v[218:221], 0
	v_mfma_f32_16x16x32_bf16 v[64:67], v[182:185], v[218:221], 0
	v_mfma_f32_16x16x32_bf16 v[120:123], v[178:181], v[198:201], v[120:123]
	v_mfma_f32_16x16x32_bf16 v[112:115], v[186:189], v[198:201], v[112:115]
	v_mfma_f32_16x16x32_bf16 v[104:107], v[178:181], v[206:209], v[104:107]
	v_mfma_f32_16x16x32_bf16 v[96:99], v[186:189], v[206:209], v[96:99]
	v_mfma_f32_16x16x32_bf16 v[88:91], v[178:181], v[214:217], v[88:91]
	v_mfma_f32_16x16x32_bf16 v[80:83], v[186:189], v[214:217], v[80:83]
	v_mfma_f32_16x16x32_bf16 v[72:75], v[178:181], v[222:225], v[72:75]
	v_mfma_f32_16x16x32_bf16 v[64:67], v[186:189], v[222:225], v[64:67]
	s_setprio 0
	s_barrier
	s_add_i32 s62, s62, s48
	s_mov_b32 m0, s62
	ds_read_b128 v[190:193], v173 offset:16384
	global_load_lds_dwordx4 v134, s[40:41]
	s_add_i32 m0, s62, 0x2000
	ds_read_b128 v[198:201], v244 offset:16384
	global_load_lds_dwordx4 v138, s[40:41]
	ds_read_b128 v[202:205], v173 offset:18432
	ds_read_b128 v[206:209], v244 offset:18432
	ds_read_b128 v[210:213], v173 offset:20480
	ds_read_b128 v[214:217], v244 offset:20480
	ds_read_b128 v[218:221], v173 offset:22528
	ds_read_b128 v[222:225], v244 offset:22528
	s_add_u32 s86, s40, 0x40000
	s_addc_u32 s87, s41, 0
	s_add_i32 s62, s63, s48
	s_waitcnt vmcnt(4)
	s_waitcnt lgkmcnt(0)
	s_barrier
	s_setprio 1
	v_mfma_f32_16x16x32_bf16 v[60:63], v[128:131], v[190:193], 0
	v_mfma_f32_16x16x32_bf16 v[52:55], v[148:151], v[190:193], 0
	v_mfma_f32_16x16x32_bf16 v[44:47], v[128:131], v[202:205], 0
	s_mov_b32 m0, s62
	v_mfma_f32_16x16x32_bf16 v[36:39], v[148:151], v[202:205], 0
	v_mfma_f32_16x16x32_bf16 v[28:31], v[128:131], v[210:213], 0
	global_load_lds_dwordx4 v134, s[86:87]
	v_mfma_f32_16x16x32_bf16 v[20:23], v[148:151], v[210:213], 0
	v_mfma_f32_16x16x32_bf16 v[8:11], v[128:131], v[218:221], 0
	v_mfma_f32_16x16x32_bf16 v[4:7], v[148:151], v[218:221], 0
	v_mfma_f32_16x16x32_bf16 v[60:63], v[144:147], v[198:201], v[60:63]
	v_mfma_f32_16x16x32_bf16 v[52:55], v[152:155], v[198:201], v[52:55]
	v_mfma_f32_16x16x32_bf16 v[44:47], v[144:147], v[206:209], v[44:47]
	s_add_i32 m0, s62, 0x2000
	v_mfma_f32_16x16x32_bf16 v[36:39], v[152:155], v[206:209], v[36:39]
	v_mfma_f32_16x16x32_bf16 v[28:31], v[144:147], v[214:217], v[28:31]
	global_load_lds_dwordx4 v138, s[86:87]
	v_mfma_f32_16x16x32_bf16 v[20:23], v[152:155], v[214:217], v[20:23]
	v_mfma_f32_16x16x32_bf16 v[8:11], v[144:147], v[222:225], v[8:11]
	v_mfma_f32_16x16x32_bf16 v[4:7], v[152:155], v[222:225], v[4:7]
	s_setprio 0
	s_setprio 1
	v_mfma_f32_16x16x32_bf16 v[56:59], v[174:177], v[190:193], 0
	v_mfma_f32_16x16x32_bf16 v[48:51], v[182:185], v[190:193], 0
	v_mfma_f32_16x16x32_bf16 v[40:43], v[174:177], v[202:205], 0
	v_mfma_f32_16x16x32_bf16 v[32:35], v[182:185], v[202:205], 0
	v_mfma_f32_16x16x32_bf16 v[24:27], v[174:177], v[210:213], 0
	v_mfma_f32_16x16x32_bf16 v[16:19], v[182:185], v[210:213], 0
	v_mfma_f32_16x16x32_bf16 v[12:15], v[174:177], v[218:221], 0
	v_mfma_f32_16x16x32_bf16 v[0:3], v[182:185], v[218:221], 0
	v_mfma_f32_16x16x32_bf16 v[56:59], v[178:181], v[198:201], v[56:59]
	v_mfma_f32_16x16x32_bf16 v[48:51], v[186:189], v[198:201], v[48:51]
	v_mfma_f32_16x16x32_bf16 v[40:43], v[178:181], v[206:209], v[40:43]
	v_mfma_f32_16x16x32_bf16 v[32:35], v[186:189], v[206:209], v[32:35]
	v_mfma_f32_16x16x32_bf16 v[24:27], v[178:181], v[214:217], v[24:27]
	v_mfma_f32_16x16x32_bf16 v[16:19], v[186:189], v[214:217], v[16:19]
	v_mfma_f32_16x16x32_bf16 v[12:15], v[178:181], v[222:225], v[12:15]
	v_mfma_f32_16x16x32_bf16 v[0:3], v[186:189], v[222:225], v[0:3]
	s_setprio 0
	s_barrier
	s_add_i32 s62, 0, 0x18000
	s_add_i32 s63, 0, 0x1c000
	s_mov_b32 m0, s51
	v_add_u32_e32 v152, s62, v172
	v_add_u32_e32 v158, s63, v172
	v_add_u32_e32 v245, s62, v243
	v_add_u32_e32 v246, s63, v243
	global_load_lds_dwordx4 v132, s[42:43]
	s_mov_b32 m0, s60
	ds_read_b128 v[128:131], v152
	global_load_lds_dwordx4 v136, s[42:43]
	ds_read_b128 v[144:147], v245
	ds_read_b128 v[148:151], v152 offset:2048
	ds_read_b128 v[152:155], v245 offset:2048
	ds_read_b128 v[174:177], v158
	ds_read_b128 v[178:181], v246
	ds_read_b128 v[182:185], v158 offset:2048
	ds_read_b128 v[186:189], v246 offset:2048
	ds_read_b128 v[190:193], v173 offset:32768
	ds_read_b128 v[198:201], v244 offset:32768
	ds_read_b128 v[202:205], v173 offset:34816
	ds_read_b128 v[206:209], v244 offset:34816
	ds_read_b128 v[210:213], v173 offset:36864
	ds_read_b128 v[214:217], v244 offset:36864
	ds_read_b128 v[218:221], v173 offset:38912
	ds_read_b128 v[222:225], v244 offset:38912
	s_add_u32 s42, s42, 0x40000
	s_addc_u32 s43, s43, 0
	s_waitcnt vmcnt(6)
	s_waitcnt lgkmcnt(0)
	s_barrier
	s_setprio 1
	v_mfma_f32_16x16x32_bf16 v[124:127], v[128:131], v[190:193], v[124:127]
	v_mfma_f32_16x16x32_bf16 v[116:119], v[148:151], v[190:193], v[116:119]
	v_mfma_f32_16x16x32_bf16 v[108:111], v[128:131], v[202:205], v[108:111]
	s_mov_b32 m0, s61
	v_mfma_f32_16x16x32_bf16 v[100:103], v[148:151], v[202:205], v[100:103]
	v_mfma_f32_16x16x32_bf16 v[92:95], v[128:131], v[210:213], v[92:95]
	global_load_lds_dwordx4 v132, s[42:43]
	v_mfma_f32_16x16x32_bf16 v[84:87], v[148:151], v[210:213], v[84:87]
	v_mfma_f32_16x16x32_bf16 v[76:79], v[128:131], v[218:221], v[76:79]
	v_mfma_f32_16x16x32_bf16 v[68:71], v[148:151], v[218:221], v[68:71]
	v_mfma_f32_16x16x32_bf16 v[124:127], v[144:147], v[198:201], v[124:127]
	v_mfma_f32_16x16x32_bf16 v[116:119], v[152:155], v[198:201], v[116:119]
	v_mfma_f32_16x16x32_bf16 v[108:111], v[144:147], v[206:209], v[108:111]
	s_mov_b32 m0, s64
	v_mfma_f32_16x16x32_bf16 v[100:103], v[152:155], v[206:209], v[100:103]
	v_mfma_f32_16x16x32_bf16 v[92:95], v[144:147], v[214:217], v[92:95]
	global_load_lds_dwordx4 v136, s[42:43]
	v_mfma_f32_16x16x32_bf16 v[84:87], v[152:155], v[214:217], v[84:87]
	v_mfma_f32_16x16x32_bf16 v[76:79], v[144:147], v[222:225], v[76:79]
	v_mfma_f32_16x16x32_bf16 v[68:71], v[152:155], v[222:225], v[68:71]
	s_setprio 0
	s_setprio 1
	v_mfma_f32_16x16x32_bf16 v[120:123], v[174:177], v[190:193], v[120:123]
	v_mfma_f32_16x16x32_bf16 v[112:115], v[182:185], v[190:193], v[112:115]
	v_mfma_f32_16x16x32_bf16 v[104:107], v[174:177], v[202:205], v[104:107]
	v_mfma_f32_16x16x32_bf16 v[96:99], v[182:185], v[202:205], v[96:99]
	v_mfma_f32_16x16x32_bf16 v[88:91], v[174:177], v[210:213], v[88:91]
	v_mfma_f32_16x16x32_bf16 v[80:83], v[182:185], v[210:213], v[80:83]
	v_mfma_f32_16x16x32_bf16 v[72:75], v[174:177], v[218:221], v[72:75]
	v_mfma_f32_16x16x32_bf16 v[64:67], v[182:185], v[218:221], v[64:67]
	v_mfma_f32_16x16x32_bf16 v[120:123], v[178:181], v[198:201], v[120:123]
	v_mfma_f32_16x16x32_bf16 v[112:115], v[186:189], v[198:201], v[112:115]
	v_mfma_f32_16x16x32_bf16 v[104:107], v[178:181], v[206:209], v[104:107]
	v_mfma_f32_16x16x32_bf16 v[96:99], v[186:189], v[206:209], v[96:99]
	v_mfma_f32_16x16x32_bf16 v[88:91], v[178:181], v[214:217], v[88:91]
	v_mfma_f32_16x16x32_bf16 v[80:83], v[186:189], v[214:217], v[80:83]
	v_mfma_f32_16x16x32_bf16 v[72:75], v[178:181], v[222:225], v[72:75]
	v_mfma_f32_16x16x32_bf16 v[64:67], v[186:189], v[222:225], v[64:67]
	s_setprio 0
	s_barrier
	s_add_i32 s42, s62, s48
	s_add_u32 s40, s40, 0x80
	s_addc_u32 s41, s41, 0
	s_mov_b32 m0, s42
	ds_read_b128 v[190:193], v173 offset:49152
	global_load_lds_dwordx4 v134, s[40:41]
	s_add_i32 m0, s42, 0x2000
	ds_read_b128 v[198:201], v244 offset:49152
	global_load_lds_dwordx4 v138, s[40:41]
	ds_read_b128 v[202:205], v173 offset:51200
	ds_read_b128 v[206:209], v244 offset:51200
	ds_read_b128 v[210:213], v173 offset:53248
	ds_read_b128 v[214:217], v244 offset:53248
	ds_read_b128 v[218:221], v173 offset:55296
	ds_read_b128 v[222:225], v244 offset:55296
	s_add_u32 s40, s40, 0x40000
	s_addc_u32 s41, s41, 0
	s_add_i32 s42, s63, s48
	s_waitcnt vmcnt(4)
	s_waitcnt lgkmcnt(0)
	s_barrier
	s_setprio 1
	v_mfma_f32_16x16x32_bf16 v[60:63], v[128:131], v[190:193], v[60:63]
	v_mfma_f32_16x16x32_bf16 v[52:55], v[148:151], v[190:193], v[52:55]
	v_mfma_f32_16x16x32_bf16 v[44:47], v[128:131], v[202:205], v[44:47]
	s_mov_b32 m0, s42
	v_mfma_f32_16x16x32_bf16 v[36:39], v[148:151], v[202:205], v[36:39]
	v_mfma_f32_16x16x32_bf16 v[28:31], v[128:131], v[210:213], v[28:31]
	global_load_lds_dwordx4 v134, s[40:41]
	v_mfma_f32_16x16x32_bf16 v[20:23], v[148:151], v[210:213], v[20:23]
	v_mfma_f32_16x16x32_bf16 v[8:11], v[128:131], v[218:221], v[8:11]
	v_mfma_f32_16x16x32_bf16 v[4:7], v[148:151], v[218:221], v[4:7]
	v_mfma_f32_16x16x32_bf16 v[60:63], v[144:147], v[198:201], v[60:63]
	v_mfma_f32_16x16x32_bf16 v[52:55], v[152:155], v[198:201], v[52:55]
	v_mfma_f32_16x16x32_bf16 v[44:47], v[144:147], v[206:209], v[44:47]
	s_add_i32 m0, s42, 0x2000
	v_mfma_f32_16x16x32_bf16 v[36:39], v[152:155], v[206:209], v[36:39]
	v_mfma_f32_16x16x32_bf16 v[28:31], v[144:147], v[214:217], v[28:31]
	global_load_lds_dwordx4 v138, s[40:41]
	v_mfma_f32_16x16x32_bf16 v[20:23], v[152:155], v[214:217], v[20:23]
	v_mfma_f32_16x16x32_bf16 v[8:11], v[144:147], v[222:225], v[8:11]
	v_mfma_f32_16x16x32_bf16 v[4:7], v[152:155], v[222:225], v[4:7]
	s_setprio 0
	s_setprio 1
	v_mfma_f32_16x16x32_bf16 v[56:59], v[174:177], v[190:193], v[56:59]
	v_mfma_f32_16x16x32_bf16 v[48:51], v[182:185], v[190:193], v[48:51]
	v_mfma_f32_16x16x32_bf16 v[40:43], v[174:177], v[202:205], v[40:43]
	v_mfma_f32_16x16x32_bf16 v[32:35], v[182:185], v[202:205], v[32:35]
	v_mfma_f32_16x16x32_bf16 v[24:27], v[174:177], v[210:213], v[24:27]
	v_mfma_f32_16x16x32_bf16 v[16:19], v[182:185], v[210:213], v[16:19]
	v_mfma_f32_16x16x32_bf16 v[12:15], v[174:177], v[218:221], v[12:15]
	v_mfma_f32_16x16x32_bf16 v[0:3], v[182:185], v[218:221], v[0:3]
	v_mfma_f32_16x16x32_bf16 v[56:59], v[178:181], v[198:201], v[56:59]
	v_mfma_f32_16x16x32_bf16 v[48:51], v[186:189], v[198:201], v[48:51]
	v_mfma_f32_16x16x32_bf16 v[40:43], v[178:181], v[206:209], v[40:43]
	v_mfma_f32_16x16x32_bf16 v[32:35], v[186:189], v[206:209], v[32:35]
	v_mfma_f32_16x16x32_bf16 v[24:27], v[178:181], v[214:217], v[24:27]
	v_mfma_f32_16x16x32_bf16 v[16:19], v[186:189], v[214:217], v[16:19]
	v_mfma_f32_16x16x32_bf16 v[12:15], v[178:181], v[222:225], v[12:15]
	v_mfma_f32_16x16x32_bf16 v[0:3], v[186:189], v[222:225], v[0:3]
	s_setprio 0
	s_barrier
	s_add_i32 s85, s85, 2
	s_add_u32 s34, s34, 0x100
	s_addc_u32 s35, s35, 0
	s_add_u32 s83, s83, 0x100
	s_addc_u32 s84, s84, 0
.LBB0_629:
	s_add_u32 s40, s34, 0xfffc0080
	s_addc_u32 s41, s35, -1
	s_add_i32 s62, 0, 0x10000
	s_cmp_eq_u32 s85, 12
	s_cselect_b32 s43, s13, s41
	s_cselect_b32 s42, s29, s40
	s_cselect_b32 s41, s5, s84
	s_cselect_b32 s40, s82, s83
	s_add_i32 s63, 0, 0x14000
	s_add_u32 s86, s34, 0xfffc0000
	s_addc_u32 s87, s35, -1
	s_mov_b32 m0, s76
	v_add_u32_e32 v152, s62, v172
	v_add_u32_e32 v158, s63, v172
	v_add_u32_e32 v245, s62, v243
	v_add_u32_e32 v246, s63, v243
	global_load_lds_dwordx4 v132, s[86:87]
	s_mov_b32 m0, s77
	ds_read_b128 v[128:131], v152
	global_load_lds_dwordx4 v136, s[86:87]
	ds_read_b128 v[144:147], v245
	ds_read_b128 v[148:151], v152 offset:2048
	ds_read_b128 v[152:155], v245 offset:2048
	ds_read_b128 v[174:177], v158
	ds_read_b128 v[178:181], v246
	ds_read_b128 v[182:185], v158 offset:2048
	ds_read_b128 v[186:189], v246 offset:2048
	ds_read_b128 v[190:193], v173
	ds_read_b128 v[198:201], v244
	ds_read_b128 v[202:205], v173 offset:2048
	ds_read_b128 v[206:209], v244 offset:2048
	ds_read_b128 v[210:213], v173 offset:4096
	ds_read_b128 v[214:217], v244 offset:4096
	ds_read_b128 v[218:221], v173 offset:6144
	ds_read_b128 v[222:225], v244 offset:6144
	s_waitcnt vmcnt(6)
	s_waitcnt lgkmcnt(0)
	s_barrier
	s_setprio 1
	v_mfma_f32_16x16x32_bf16 v[124:127], v[128:131], v[190:193], v[124:127]
	v_mfma_f32_16x16x32_bf16 v[116:119], v[148:151], v[190:193], v[116:119]
	v_mfma_f32_16x16x32_bf16 v[108:111], v[128:131], v[202:205], v[108:111]
	s_add_i32 m0, s51, 0xc000
	v_mfma_f32_16x16x32_bf16 v[100:103], v[148:151], v[202:205], v[100:103]
	v_mfma_f32_16x16x32_bf16 v[92:95], v[128:131], v[210:213], v[92:95]
	global_load_lds_dwordx4 v132, s[34:35]
	v_mfma_f32_16x16x32_bf16 v[84:87], v[148:151], v[210:213], v[84:87]
	v_mfma_f32_16x16x32_bf16 v[76:79], v[128:131], v[218:221], v[76:79]
	v_mfma_f32_16x16x32_bf16 v[68:71], v[148:151], v[218:221], v[68:71]
	v_mfma_f32_16x16x32_bf16 v[124:127], v[144:147], v[198:201], v[124:127]
	v_mfma_f32_16x16x32_bf16 v[116:119], v[152:155], v[198:201], v[116:119]
	v_mfma_f32_16x16x32_bf16 v[108:111], v[144:147], v[206:209], v[108:111]
	s_add_i32 m0, s51, 0xe000
	v_mfma_f32_16x16x32_bf16 v[100:103], v[152:155], v[206:209], v[100:103]
	v_mfma_f32_16x16x32_bf16 v[92:95], v[144:147], v[214:217], v[92:95]
	global_load_lds_dwordx4 v136, s[34:35]
	v_mfma_f32_16x16x32_bf16 v[84:87], v[152:155], v[214:217], v[84:87]
	v_mfma_f32_16x16x32_bf16 v[76:79], v[144:147], v[222:225], v[76:79]
	v_mfma_f32_16x16x32_bf16 v[68:71], v[152:155], v[222:225], v[68:71]
	s_setprio 0
	s_setprio 1
	v_mfma_f32_16x16x32_bf16 v[120:123], v[174:177], v[190:193], v[120:123]
	v_mfma_f32_16x16x32_bf16 v[112:115], v[182:185], v[190:193], v[112:115]
	v_mfma_f32_16x16x32_bf16 v[104:107], v[174:177], v[202:205], v[104:107]
	v_mfma_f32_16x16x32_bf16 v[96:99], v[182:185], v[202:205], v[96:99]
	v_mfma_f32_16x16x32_bf16 v[88:91], v[174:177], v[210:213], v[88:91]
	v_mfma_f32_16x16x32_bf16 v[80:83], v[182:185], v[210:213], v[80:83]
	v_mfma_f32_16x16x32_bf16 v[72:75], v[174:177], v[218:221], v[72:75]
	v_mfma_f32_16x16x32_bf16 v[64:67], v[182:185], v[218:221], v[64:67]
	v_mfma_f32_16x16x32_bf16 v[120:123], v[178:181], v[198:201], v[120:123]
	v_mfma_f32_16x16x32_bf16 v[112:115], v[186:189], v[198:201], v[112:115]
	v_mfma_f32_16x16x32_bf16 v[104:107], v[178:181], v[206:209], v[104:107]
	v_mfma_f32_16x16x32_bf16 v[96:99], v[186:189], v[206:209], v[96:99]
	v_mfma_f32_16x16x32_bf16 v[88:91], v[178:181], v[214:217], v[88:91]
	v_mfma_f32_16x16x32_bf16 v[80:83], v[186:189], v[214:217], v[80:83]
	v_mfma_f32_16x16x32_bf16 v[72:75], v[178:181], v[222:225], v[72:75]
	v_mfma_f32_16x16x32_bf16 v[64:67], v[186:189], v[222:225], v[64:67]
	s_setprio 0
	s_barrier
	s_add_i32 s62, s62, s48
	s_mov_b32 m0, s62
	ds_read_b128 v[190:193], v173 offset:16384
	global_load_lds_dwordx4 v134, s[40:41]
	s_add_i32 m0, s62, 0x2000
	ds_read_b128 v[198:201], v244 offset:16384
	global_load_lds_dwordx4 v138, s[40:41]
	ds_read_b128 v[202:205], v173 offset:18432
	ds_read_b128 v[206:209], v244 offset:18432
	ds_read_b128 v[210:213], v173 offset:20480
	ds_read_b128 v[214:217], v244 offset:20480
	ds_read_b128 v[218:221], v173 offset:22528
	ds_read_b128 v[222:225], v244 offset:22528
	s_add_u32 s86, s40, 0x40000
	s_addc_u32 s87, s41, 0
	s_add_i32 s62, s63, s48
	s_waitcnt vmcnt(4)
	s_waitcnt lgkmcnt(0)
	s_barrier
	s_setprio 1
	v_mfma_f32_16x16x32_bf16 v[60:63], v[128:131], v[190:193], v[60:63]
	v_mfma_f32_16x16x32_bf16 v[52:55], v[148:151], v[190:193], v[52:55]
	v_mfma_f32_16x16x32_bf16 v[44:47], v[128:131], v[202:205], v[44:47]
	s_mov_b32 m0, s62
	v_mfma_f32_16x16x32_bf16 v[36:39], v[148:151], v[202:205], v[36:39]
	v_mfma_f32_16x16x32_bf16 v[28:31], v[128:131], v[210:213], v[28:31]
	global_load_lds_dwordx4 v134, s[86:87]
	v_mfma_f32_16x16x32_bf16 v[20:23], v[148:151], v[210:213], v[20:23]
	v_mfma_f32_16x16x32_bf16 v[8:11], v[128:131], v[218:221], v[8:11]
	v_mfma_f32_16x16x32_bf16 v[4:7], v[148:151], v[218:221], v[4:7]
	v_mfma_f32_16x16x32_bf16 v[60:63], v[144:147], v[198:201], v[60:63]
	v_mfma_f32_16x16x32_bf16 v[52:55], v[152:155], v[198:201], v[52:55]
	v_mfma_f32_16x16x32_bf16 v[44:47], v[144:147], v[206:209], v[44:47]
	s_add_i32 m0, s62, 0x2000
	v_mfma_f32_16x16x32_bf16 v[36:39], v[152:155], v[206:209], v[36:39]
	v_mfma_f32_16x16x32_bf16 v[28:31], v[144:147], v[214:217], v[28:31]
	global_load_lds_dwordx4 v138, s[86:87]
	v_mfma_f32_16x16x32_bf16 v[20:23], v[152:155], v[214:217], v[20:23]
	v_mfma_f32_16x16x32_bf16 v[8:11], v[144:147], v[222:225], v[8:11]
	v_mfma_f32_16x16x32_bf16 v[4:7], v[152:155], v[222:225], v[4:7]
	s_setprio 0
	s_setprio 1
	v_mfma_f32_16x16x32_bf16 v[56:59], v[174:177], v[190:193], v[56:59]
	v_mfma_f32_16x16x32_bf16 v[48:51], v[182:185], v[190:193], v[48:51]
	v_mfma_f32_16x16x32_bf16 v[40:43], v[174:177], v[202:205], v[40:43]
	v_mfma_f32_16x16x32_bf16 v[32:35], v[182:185], v[202:205], v[32:35]
	v_mfma_f32_16x16x32_bf16 v[24:27], v[174:177], v[210:213], v[24:27]
	v_mfma_f32_16x16x32_bf16 v[16:19], v[182:185], v[210:213], v[16:19]
	v_mfma_f32_16x16x32_bf16 v[12:15], v[174:177], v[218:221], v[12:15]
	v_mfma_f32_16x16x32_bf16 v[0:3], v[182:185], v[218:221], v[0:3]
	v_mfma_f32_16x16x32_bf16 v[56:59], v[178:181], v[198:201], v[56:59]
	v_mfma_f32_16x16x32_bf16 v[48:51], v[186:189], v[198:201], v[48:51]
	v_mfma_f32_16x16x32_bf16 v[40:43], v[178:181], v[206:209], v[40:43]
	v_mfma_f32_16x16x32_bf16 v[32:35], v[186:189], v[206:209], v[32:35]
	v_mfma_f32_16x16x32_bf16 v[24:27], v[178:181], v[214:217], v[24:27]
	v_mfma_f32_16x16x32_bf16 v[16:19], v[186:189], v[214:217], v[16:19]
	v_mfma_f32_16x16x32_bf16 v[12:15], v[178:181], v[222:225], v[12:15]
	v_mfma_f32_16x16x32_bf16 v[0:3], v[186:189], v[222:225], v[0:3]
	s_setprio 0
	s_barrier
	s_add_i32 s62, 0, 0x18000
	s_add_i32 s63, 0, 0x1c000
	s_mov_b32 m0, s51
	v_add_u32_e32 v152, s62, v172
	v_add_u32_e32 v158, s63, v172
	v_add_u32_e32 v245, s62, v243
	v_add_u32_e32 v246, s63, v243
	global_load_lds_dwordx4 v132, s[42:43]
	s_mov_b32 m0, s60
	ds_read_b128 v[128:131], v152
	global_load_lds_dwordx4 v136, s[42:43]
	ds_read_b128 v[144:147], v245
	ds_read_b128 v[148:151], v152 offset:2048
	ds_read_b128 v[152:155], v245 offset:2048
	ds_read_b128 v[174:177], v158
	ds_read_b128 v[178:181], v246
	ds_read_b128 v[182:185], v158 offset:2048
	ds_read_b128 v[186:189], v246 offset:2048
	ds_read_b128 v[190:193], v173 offset:32768
	ds_read_b128 v[198:201], v244 offset:32768
	ds_read_b128 v[202:205], v173 offset:34816
	ds_read_b128 v[206:209], v244 offset:34816
	ds_read_b128 v[210:213], v173 offset:36864
	ds_read_b128 v[214:217], v244 offset:36864
	ds_read_b128 v[218:221], v173 offset:38912
	ds_read_b128 v[222:225], v244 offset:38912
	s_add_u32 s42, s42, 0x40000
	s_addc_u32 s43, s43, 0
	s_waitcnt vmcnt(6)
	s_waitcnt lgkmcnt(0)
	s_barrier
	s_setprio 1
	v_mfma_f32_16x16x32_bf16 v[124:127], v[128:131], v[190:193], v[124:127]
	v_mfma_f32_16x16x32_bf16 v[116:119], v[148:151], v[190:193], v[116:119]
	v_mfma_f32_16x16x32_bf16 v[108:111], v[128:131], v[202:205], v[108:111]
	s_mov_b32 m0, s61
	v_mfma_f32_16x16x32_bf16 v[100:103], v[148:151], v[202:205], v[100:103]
	v_mfma_f32_16x16x32_bf16 v[92:95], v[128:131], v[210:213], v[92:95]
	global_load_lds_dwordx4 v132, s[42:43]
	v_mfma_f32_16x16x32_bf16 v[84:87], v[148:151], v[210:213], v[84:87]
	v_mfma_f32_16x16x32_bf16 v[76:79], v[128:131], v[218:221], v[76:79]
	v_mfma_f32_16x16x32_bf16 v[68:71], v[148:151], v[218:221], v[68:71]
	v_mfma_f32_16x16x32_bf16 v[124:127], v[144:147], v[198:201], v[124:127]
	v_mfma_f32_16x16x32_bf16 v[116:119], v[152:155], v[198:201], v[116:119]
	v_mfma_f32_16x16x32_bf16 v[108:111], v[144:147], v[206:209], v[108:111]
	s_mov_b32 m0, s64
	v_mfma_f32_16x16x32_bf16 v[100:103], v[152:155], v[206:209], v[100:103]
	v_mfma_f32_16x16x32_bf16 v[92:95], v[144:147], v[214:217], v[92:95]
	global_load_lds_dwordx4 v136, s[42:43]
	v_mfma_f32_16x16x32_bf16 v[84:87], v[152:155], v[214:217], v[84:87]
	v_mfma_f32_16x16x32_bf16 v[76:79], v[144:147], v[222:225], v[76:79]
	v_mfma_f32_16x16x32_bf16 v[68:71], v[152:155], v[222:225], v[68:71]
	s_setprio 0
	s_setprio 1
	v_mfma_f32_16x16x32_bf16 v[120:123], v[174:177], v[190:193], v[120:123]
	v_mfma_f32_16x16x32_bf16 v[112:115], v[182:185], v[190:193], v[112:115]
	v_mfma_f32_16x16x32_bf16 v[104:107], v[174:177], v[202:205], v[104:107]
	v_mfma_f32_16x16x32_bf16 v[96:99], v[182:185], v[202:205], v[96:99]
	v_mfma_f32_16x16x32_bf16 v[88:91], v[174:177], v[210:213], v[88:91]
	v_mfma_f32_16x16x32_bf16 v[80:83], v[182:185], v[210:213], v[80:83]
	v_mfma_f32_16x16x32_bf16 v[72:75], v[174:177], v[218:221], v[72:75]
	v_mfma_f32_16x16x32_bf16 v[64:67], v[182:185], v[218:221], v[64:67]
	v_mfma_f32_16x16x32_bf16 v[120:123], v[178:181], v[198:201], v[120:123]
	v_mfma_f32_16x16x32_bf16 v[112:115], v[186:189], v[198:201], v[112:115]
	v_mfma_f32_16x16x32_bf16 v[104:107], v[178:181], v[206:209], v[104:107]
	v_mfma_f32_16x16x32_bf16 v[96:99], v[186:189], v[206:209], v[96:99]
	v_mfma_f32_16x16x32_bf16 v[88:91], v[178:181], v[214:217], v[88:91]
	v_mfma_f32_16x16x32_bf16 v[80:83], v[186:189], v[214:217], v[80:83]
	v_mfma_f32_16x16x32_bf16 v[72:75], v[178:181], v[222:225], v[72:75]
	v_mfma_f32_16x16x32_bf16 v[64:67], v[186:189], v[222:225], v[64:67]
	s_setprio 0
	s_barrier
	s_add_i32 s42, s62, s48
	s_add_u32 s40, s40, 0x80
	s_addc_u32 s41, s41, 0
	s_mov_b32 m0, s42
	ds_read_b128 v[190:193], v173 offset:49152
	global_load_lds_dwordx4 v134, s[40:41]
	s_add_i32 m0, s42, 0x2000
	ds_read_b128 v[198:201], v244 offset:49152
	global_load_lds_dwordx4 v138, s[40:41]
	ds_read_b128 v[202:205], v173 offset:51200
	ds_read_b128 v[206:209], v244 offset:51200
	ds_read_b128 v[210:213], v173 offset:53248
	ds_read_b128 v[214:217], v244 offset:53248
	ds_read_b128 v[218:221], v173 offset:55296
	ds_read_b128 v[222:225], v244 offset:55296
	s_add_u32 s40, s40, 0x40000
	s_addc_u32 s41, s41, 0
	s_add_i32 s42, s63, s48
	s_waitcnt vmcnt(4)
	s_waitcnt lgkmcnt(0)
	s_barrier
	s_setprio 1
	v_mfma_f32_16x16x32_bf16 v[60:63], v[128:131], v[190:193], v[60:63]
	v_mfma_f32_16x16x32_bf16 v[52:55], v[148:151], v[190:193], v[52:55]
	v_mfma_f32_16x16x32_bf16 v[44:47], v[128:131], v[202:205], v[44:47]
	s_mov_b32 m0, s42
	v_mfma_f32_16x16x32_bf16 v[36:39], v[148:151], v[202:205], v[36:39]
	v_mfma_f32_16x16x32_bf16 v[28:31], v[128:131], v[210:213], v[28:31]
	global_load_lds_dwordx4 v134, s[40:41]
	v_mfma_f32_16x16x32_bf16 v[20:23], v[148:151], v[210:213], v[20:23]
	v_mfma_f32_16x16x32_bf16 v[8:11], v[128:131], v[218:221], v[8:11]
	v_mfma_f32_16x16x32_bf16 v[4:7], v[148:151], v[218:221], v[4:7]
	v_mfma_f32_16x16x32_bf16 v[60:63], v[144:147], v[198:201], v[60:63]
	v_mfma_f32_16x16x32_bf16 v[52:55], v[152:155], v[198:201], v[52:55]
	v_mfma_f32_16x16x32_bf16 v[44:47], v[144:147], v[206:209], v[44:47]
	s_add_i32 m0, s42, 0x2000
	v_mfma_f32_16x16x32_bf16 v[36:39], v[152:155], v[206:209], v[36:39]
	v_mfma_f32_16x16x32_bf16 v[28:31], v[144:147], v[214:217], v[28:31]
	global_load_lds_dwordx4 v138, s[40:41]
	v_mfma_f32_16x16x32_bf16 v[20:23], v[152:155], v[214:217], v[20:23]
	v_mfma_f32_16x16x32_bf16 v[8:11], v[144:147], v[222:225], v[8:11]
	v_mfma_f32_16x16x32_bf16 v[4:7], v[152:155], v[222:225], v[4:7]
	s_setprio 0
	s_setprio 1
	v_mfma_f32_16x16x32_bf16 v[56:59], v[174:177], v[190:193], v[56:59]
	v_mfma_f32_16x16x32_bf16 v[48:51], v[182:185], v[190:193], v[48:51]
	v_mfma_f32_16x16x32_bf16 v[40:43], v[174:177], v[202:205], v[40:43]
	v_mfma_f32_16x16x32_bf16 v[32:35], v[182:185], v[202:205], v[32:35]
	v_mfma_f32_16x16x32_bf16 v[24:27], v[174:177], v[210:213], v[24:27]
	v_mfma_f32_16x16x32_bf16 v[16:19], v[182:185], v[210:213], v[16:19]
	v_mfma_f32_16x16x32_bf16 v[12:15], v[174:177], v[218:221], v[12:15]
	v_mfma_f32_16x16x32_bf16 v[0:3], v[182:185], v[218:221], v[0:3]
	v_mfma_f32_16x16x32_bf16 v[56:59], v[178:181], v[198:201], v[56:59]
	v_mfma_f32_16x16x32_bf16 v[48:51], v[186:189], v[198:201], v[48:51]
	v_mfma_f32_16x16x32_bf16 v[40:43], v[178:181], v[206:209], v[40:43]
	v_mfma_f32_16x16x32_bf16 v[32:35], v[186:189], v[206:209], v[32:35]
	v_mfma_f32_16x16x32_bf16 v[24:27], v[178:181], v[214:217], v[24:27]
	v_mfma_f32_16x16x32_bf16 v[16:19], v[186:189], v[214:217], v[16:19]
	v_mfma_f32_16x16x32_bf16 v[12:15], v[178:181], v[222:225], v[12:15]
	v_mfma_f32_16x16x32_bf16 v[0:3], v[186:189], v[222:225], v[0:3]
	s_setprio 0
	s_barrier
	s_add_i32 s85, s85, 2
	s_add_u32 s34, s34, 0x100
	s_addc_u32 s35, s35, 0
	s_add_u32 s83, s83, 0x100
	s_addc_u32 s84, s84, 0
	s_cmp_gt_u32 s85, 13
	s_cbranch_scc0 .LBB0_629
	s_and_b64 vcc, exec, s[2:3]
	s_cbranch_vccz .LBB0_632
	s_barrier

.LBB0_711:
	s_add_u32 s28, s26, 0xfffc0080
	s_addc_u32 s29, s27, -1
	s_add_i32 s62, 0, 0x10000
	s_cmp_eq_u32 s64, 12
	s_cselect_b32 s31, s50, s29
	s_cselect_b32 s30, s51, s28
	v_add_u32_e32 v144, s62, v148
	s_cselect_b32 s29, s58, s61
	s_cselect_b32 s28, s59, s60
	s_add_i32 s63, 0, 0x14000
	ds_read_b128 v[140:143], v144
	ds_read_b128 v[150:153], v144 offset:1024
	ds_read_b128 v[168:171], v144 offset:2048
	ds_read_b128 v[172:175], v144 offset:3072
	v_add_u32_e32 v144, s63, v148
	ds_read_b128 v[176:179], v144
	ds_read_b128 v[180:183], v144 offset:1024
	ds_read_b128 v[184:187], v144 offset:2048
	ds_read_b128 v[188:191], v144 offset:3072
	v_lshl_add_u64 v[144:145], s[26:27], 0, v[136:137]
	s_add_i32 m0, s1, 0xc000
	ds_read_b128 v[198:201], v149
	ds_read_b128 v[202:205], v149 offset:1024
	ds_read_b128 v[206:209], v149 offset:2048
	ds_read_b128 v[210:213], v149 offset:3072
	ds_read_b128 v[214:217], v149 offset:4096
	ds_read_b128 v[218:221], v149 offset:5120
	ds_read_b128 v[222:225], v149 offset:6144
	ds_read_b128 v[226:229], v149 offset:7168
	global_load_lds_dwordx4 v[144:145], off
	v_lshl_add_u64 v[144:145], s[26:27], 0, v[138:139]
	s_add_i32 m0, s1, 0xe000
	s_nop 0
	global_load_lds_dwordx4 v[144:145], off
	s_waitcnt vmcnt(8)
	s_waitcnt lgkmcnt(0)
	s_barrier
	s_setprio 1
	v_mfma_f32_16x16x32_bf16 v[124:127], v[140:143], v[198:201], v[124:127]
	v_mfma_f32_16x16x32_bf16 v[120:123], v[168:171], v[198:201], v[120:123]
	v_mfma_f32_16x16x32_bf16 v[108:111], v[140:143], v[206:209], v[108:111]
	v_mfma_f32_16x16x32_bf16 v[104:107], v[168:171], v[206:209], v[104:107]
	v_mfma_f32_16x16x32_bf16 v[92:95], v[140:143], v[214:217], v[92:95]
	v_mfma_f32_16x16x32_bf16 v[88:91], v[168:171], v[214:217], v[88:91]
	v_mfma_f32_16x16x32_bf16 v[76:79], v[140:143], v[222:225], v[76:79]
	v_mfma_f32_16x16x32_bf16 v[72:75], v[168:171], v[222:225], v[72:75]
	v_mfma_f32_16x16x32_bf16 v[124:127], v[150:153], v[202:205], v[124:127]
	v_mfma_f32_16x16x32_bf16 v[120:123], v[172:175], v[202:205], v[120:123]
	v_mfma_f32_16x16x32_bf16 v[108:111], v[150:153], v[210:213], v[108:111]
	v_mfma_f32_16x16x32_bf16 v[104:107], v[172:175], v[210:213], v[104:107]
	v_mfma_f32_16x16x32_bf16 v[92:95], v[150:153], v[218:221], v[92:95]
	v_mfma_f32_16x16x32_bf16 v[88:91], v[172:175], v[218:221], v[88:91]
	v_mfma_f32_16x16x32_bf16 v[76:79], v[150:153], v[226:229], v[76:79]
	v_mfma_f32_16x16x32_bf16 v[72:75], v[172:175], v[226:229], v[72:75]
	s_setprio 0
	s_setprio 1
	v_mfma_f32_16x16x32_bf16 v[116:119], v[176:179], v[198:201], v[116:119]
	v_mfma_f32_16x16x32_bf16 v[112:115], v[184:187], v[198:201], v[112:115]
	v_mfma_f32_16x16x32_bf16 v[100:103], v[176:179], v[206:209], v[100:103]
	v_mfma_f32_16x16x32_bf16 v[96:99], v[184:187], v[206:209], v[96:99]
	v_mfma_f32_16x16x32_bf16 v[84:87], v[176:179], v[214:217], v[84:87]
	v_mfma_f32_16x16x32_bf16 v[80:83], v[184:187], v[214:217], v[80:83]
	v_mfma_f32_16x16x32_bf16 v[68:71], v[176:179], v[222:225], v[68:71]
	v_mfma_f32_16x16x32_bf16 v[64:67], v[184:187], v[222:225], v[64:67]
	v_mfma_f32_16x16x32_bf16 v[116:119], v[180:183], v[202:205], v[116:119]
	v_mfma_f32_16x16x32_bf16 v[112:115], v[188:191], v[202:205], v[112:115]
	v_mfma_f32_16x16x32_bf16 v[100:103], v[180:183], v[210:213], v[100:103]
	v_mfma_f32_16x16x32_bf16 v[96:99], v[188:191], v[210:213], v[96:99]
	v_mfma_f32_16x16x32_bf16 v[84:87], v[180:183], v[218:221], v[84:87]
	v_mfma_f32_16x16x32_bf16 v[80:83], v[188:191], v[218:221], v[80:83]
	v_mfma_f32_16x16x32_bf16 v[68:71], v[180:183], v[226:229], v[68:71]
	v_mfma_f32_16x16x32_bf16 v[64:67], v[188:191], v[226:229], v[64:67]
	s_setprio 0
	s_barrier
	s_add_i32 s62, s62, s36
	v_lshl_add_u64 v[144:145], s[28:29], 0, v[132:133]
	s_mov_b32 m0, s62
	ds_read_b128 v[198:201], v149 offset:16384
	ds_read_b128 v[202:205], v149 offset:17408
	ds_read_b128 v[206:209], v149 offset:18432
	ds_read_b128 v[210:213], v149 offset:19456
	ds_read_b128 v[214:217], v149 offset:20480
	ds_read_b128 v[218:221], v149 offset:21504
	ds_read_b128 v[222:225], v149 offset:22528
	ds_read_b128 v[226:229], v149 offset:23552
	global_load_lds_dwordx4 v[144:145], off
	s_add_i32 m0, s62, 0x2000
	s_add_u32 s76, s28, 0x40000
	v_lshl_add_u64 v[154:155], s[28:29], 0, v[128:129]
	s_addc_u32 s77, s29, 0
	s_add_i32 s62, s63, s36
	global_load_lds_dwordx4 v[154:155], off
	v_lshl_add_u64 v[192:193], s[76:77], 0, v[132:133]
	s_mov_b32 m0, s62
	v_lshl_add_u64 v[230:231], s[30:31], 0, v[130:131]
	global_load_lds_dwordx4 v[192:193], off
	v_lshl_add_u64 v[192:193], s[76:77], 0, v[128:129]
	s_add_i32 m0, s62, 0x2000
	s_nop 0
	global_load_lds_dwordx4 v[192:193], off
	v_lshl_add_u64 v[192:193], s[30:31], 0, v[134:135]
	s_mov_b32 m0, s1
	s_nop 0
	global_load_lds_dwordx4 v[192:193], off
	s_mov_b32 m0, s42
	s_nop 0
	global_load_lds_dwordx4 v[230:231], off
	s_waitcnt vmcnt(8)
	s_waitcnt lgkmcnt(0)
	s_barrier
	s_setprio 1
	v_mfma_f32_16x16x32_bf16 v[60:63], v[140:143], v[198:201], v[60:63]
	v_mfma_f32_16x16x32_bf16 v[56:59], v[168:171], v[198:201], v[56:59]
	v_mfma_f32_16x16x32_bf16 v[44:47], v[140:143], v[206:209], v[44:47]
	v_mfma_f32_16x16x32_bf16 v[40:43], v[168:171], v[206:209], v[40:43]
	v_mfma_f32_16x16x32_bf16 v[28:31], v[140:143], v[214:217], v[28:31]
	v_mfma_f32_16x16x32_bf16 v[24:27], v[168:171], v[214:217], v[24:27]
	v_mfma_f32_16x16x32_bf16 v[12:15], v[140:143], v[222:225], v[12:15]
	v_mfma_f32_16x16x32_bf16 v[8:11], v[168:171], v[222:225], v[8:11]
	v_mfma_f32_16x16x32_bf16 v[60:63], v[150:153], v[202:205], v[60:63]
	v_mfma_f32_16x16x32_bf16 v[56:59], v[172:175], v[202:205], v[56:59]
	v_mfma_f32_16x16x32_bf16 v[44:47], v[150:153], v[210:213], v[44:47]
	v_mfma_f32_16x16x32_bf16 v[40:43], v[172:175], v[210:213], v[40:43]
	v_mfma_f32_16x16x32_bf16 v[28:31], v[150:153], v[218:221], v[28:31]
	v_mfma_f32_16x16x32_bf16 v[24:27], v[172:175], v[218:221], v[24:27]
	v_mfma_f32_16x16x32_bf16 v[12:15], v[150:153], v[226:229], v[12:15]
	v_mfma_f32_16x16x32_bf16 v[8:11], v[172:175], v[226:229], v[8:11]
	s_setprio 0
	s_setprio 1
	v_mfma_f32_16x16x32_bf16 v[52:55], v[176:179], v[198:201], v[52:55]
	v_mfma_f32_16x16x32_bf16 v[48:51], v[184:187], v[198:201], v[48:51]
	v_mfma_f32_16x16x32_bf16 v[36:39], v[176:179], v[206:209], v[36:39]
	v_mfma_f32_16x16x32_bf16 v[32:35], v[184:187], v[206:209], v[32:35]
	v_mfma_f32_16x16x32_bf16 v[20:23], v[176:179], v[214:217], v[20:23]
	v_mfma_f32_16x16x32_bf16 v[16:19], v[184:187], v[214:217], v[16:19]
	v_mfma_f32_16x16x32_bf16 v[4:7], v[176:179], v[222:225], v[4:7]
	v_mfma_f32_16x16x32_bf16 v[0:3], v[184:187], v[222:225], v[0:3]
	v_mfma_f32_16x16x32_bf16 v[52:55], v[180:183], v[202:205], v[52:55]
	v_mfma_f32_16x16x32_bf16 v[48:51], v[188:191], v[202:205], v[48:51]
	v_mfma_f32_16x16x32_bf16 v[36:39], v[180:183], v[210:213], v[36:39]
	v_mfma_f32_16x16x32_bf16 v[32:35], v[188:191], v[210:213], v[32:35]
	v_mfma_f32_16x16x32_bf16 v[20:23], v[180:183], v[218:221], v[20:23]
	v_mfma_f32_16x16x32_bf16 v[16:19], v[188:191], v[218:221], v[16:19]
	v_mfma_f32_16x16x32_bf16 v[4:7], v[180:183], v[226:229], v[4:7]
	v_mfma_f32_16x16x32_bf16 v[0:3], v[188:191], v[226:229], v[0:3]
	s_setprio 0
	s_barrier
	s_add_i32 s62, 0, 0x18000
	v_add_u32_e32 v158, s62, v148
	s_add_i32 s63, 0, 0x1c000
	ds_read_b128 v[140:143], v158
	ds_read_b128 v[150:153], v158 offset:1024
	ds_read_b128 v[168:171], v158 offset:2048
	ds_read_b128 v[172:175], v158 offset:3072
	v_add_u32_e32 v158, s63, v148
	ds_read_b128 v[176:179], v158
	ds_read_b128 v[180:183], v158 offset:1024
	ds_read_b128 v[184:187], v158 offset:2048
	ds_read_b128 v[188:191], v158 offset:3072
	s_add_u32 s30, s30, 0x40000
	s_addc_u32 s31, s31, 0
	s_mov_b32 m0, s43
	v_lshl_add_u64 v[232:233], s[30:31], 0, v[134:135]
	ds_read_b128 v[198:201], v149 offset:32768
	ds_read_b128 v[202:205], v149 offset:33792
	ds_read_b128 v[206:209], v149 offset:34816
	ds_read_b128 v[210:213], v149 offset:35840
	ds_read_b128 v[214:217], v149 offset:36864
	ds_read_b128 v[218:221], v149 offset:37888
	ds_read_b128 v[222:225], v149 offset:38912
	ds_read_b128 v[226:229], v149 offset:39936
	global_load_lds_dwordx4 v[232:233], off
	v_lshl_add_u64 v[232:233], s[30:31], 0, v[130:131]
	s_mov_b32 m0, s44
	s_nop 0
	global_load_lds_dwordx4 v[232:233], off
	s_waitcnt vmcnt(8)
	s_waitcnt lgkmcnt(0)
	s_barrier
	s_setprio 1
	v_mfma_f32_16x16x32_bf16 v[124:127], v[140:143], v[198:201], v[124:127]
	v_mfma_f32_16x16x32_bf16 v[120:123], v[168:171], v[198:201], v[120:123]
	v_mfma_f32_16x16x32_bf16 v[108:111], v[140:143], v[206:209], v[108:111]
	v_mfma_f32_16x16x32_bf16 v[104:107], v[168:171], v[206:209], v[104:107]
	v_mfma_f32_16x16x32_bf16 v[92:95], v[140:143], v[214:217], v[92:95]
	v_mfma_f32_16x16x32_bf16 v[88:91], v[168:171], v[214:217], v[88:91]
	v_mfma_f32_16x16x32_bf16 v[76:79], v[140:143], v[222:225], v[76:79]
	v_mfma_f32_16x16x32_bf16 v[72:75], v[168:171], v[222:225], v[72:75]
	v_mfma_f32_16x16x32_bf16 v[124:127], v[150:153], v[202:205], v[124:127]
	v_mfma_f32_16x16x32_bf16 v[120:123], v[172:175], v[202:205], v[120:123]
	v_mfma_f32_16x16x32_bf16 v[108:111], v[150:153], v[210:213], v[108:111]
	v_mfma_f32_16x16x32_bf16 v[104:107], v[172:175], v[210:213], v[104:107]
	v_mfma_f32_16x16x32_bf16 v[92:95], v[150:153], v[218:221], v[92:95]
	v_mfma_f32_16x16x32_bf16 v[88:91], v[172:175], v[218:221], v[88:91]
	v_mfma_f32_16x16x32_bf16 v[76:79], v[150:153], v[226:229], v[76:79]
	v_mfma_f32_16x16x32_bf16 v[72:75], v[172:175], v[226:229], v[72:75]
	s_setprio 0
	s_setprio 1
	v_mfma_f32_16x16x32_bf16 v[116:119], v[176:179], v[198:201], v[116:119]
	v_mfma_f32_16x16x32_bf16 v[112:115], v[184:187], v[198:201], v[112:115]
	v_mfma_f32_16x16x32_bf16 v[100:103], v[176:179], v[206:209], v[100:103]
	v_mfma_f32_16x16x32_bf16 v[96:99], v[184:187], v[206:209], v[96:99]
	v_mfma_f32_16x16x32_bf16 v[84:87], v[176:179], v[214:217], v[84:87]
	v_mfma_f32_16x16x32_bf16 v[80:83], v[184:187], v[214:217], v[80:83]
	v_mfma_f32_16x16x32_bf16 v[68:71], v[176:179], v[222:225], v[68:71]
	v_mfma_f32_16x16x32_bf16 v[64:67], v[184:187], v[222:225], v[64:67]
	v_mfma_f32_16x16x32_bf16 v[116:119], v[180:183], v[202:205], v[116:119]
	v_mfma_f32_16x16x32_bf16 v[112:115], v[188:191], v[202:205], v[112:115]
	v_mfma_f32_16x16x32_bf16 v[100:103], v[180:183], v[210:213], v[100:103]
	v_mfma_f32_16x16x32_bf16 v[96:99], v[188:191], v[210:213], v[96:99]
	v_mfma_f32_16x16x32_bf16 v[84:87], v[180:183], v[218:221], v[84:87]
	v_mfma_f32_16x16x32_bf16 v[80:83], v[188:191], v[218:221], v[80:83]
	v_mfma_f32_16x16x32_bf16 v[68:71], v[180:183], v[226:229], v[68:71]
	v_mfma_f32_16x16x32_bf16 v[64:67], v[188:191], v[226:229], v[64:67]
	s_setprio 0
	s_barrier
	s_add_i32 s30, s62, s36
	v_lshl_add_u64 v[144:145], v[144:145], 0, s[14:15]
	s_mov_b32 m0, s30
	ds_read_b128 v[198:201], v149 offset:49152
	ds_read_b128 v[202:205], v149 offset:50176
	ds_read_b128 v[206:209], v149 offset:51200
	ds_read_b128 v[210:213], v149 offset:52224
	ds_read_b128 v[214:217], v149 offset:53248
	ds_read_b128 v[218:221], v149 offset:54272
	ds_read_b128 v[222:225], v149 offset:55296
	ds_read_b128 v[226:229], v149 offset:56320
	global_load_lds_dwordx4 v[144:145], off
	s_add_i32 m0, s30, 0x2000
	s_add_u32 s28, s28, 0x40080
	v_lshl_add_u64 v[144:145], v[154:155], 0, s[14:15]
	s_addc_u32 s29, s29, 0
	s_add_i32 s30, s63, s36
	global_load_lds_dwordx4 v[144:145], off
	v_lshl_add_u64 v[144:145], s[28:29], 0, v[132:133]
	s_mov_b32 m0, s30
	s_nop 0
	global_load_lds_dwordx4 v[144:145], off
	v_lshl_add_u64 v[144:145], s[28:29], 0, v[128:129]
	s_add_i32 m0, s30, 0x2000
	s_nop 0
	global_load_lds_dwordx4 v[144:145], off
	v_lshl_add_u64 v[144:145], v[192:193], 0, s[14:15]
	s_mov_b32 m0, s47
	s_nop 0
	global_load_lds_dwordx4 v[144:145], off
	v_lshl_add_u64 v[144:145], v[230:231], 0, s[14:15]
	s_mov_b32 m0, s48
	s_nop 0
	global_load_lds_dwordx4 v[144:145], off
	s_waitcnt vmcnt(8)
	s_waitcnt lgkmcnt(0)
	s_barrier
	s_setprio 1
	v_mfma_f32_16x16x32_bf16 v[60:63], v[140:143], v[198:201], v[60:63]
	v_mfma_f32_16x16x32_bf16 v[56:59], v[168:171], v[198:201], v[56:59]
	v_mfma_f32_16x16x32_bf16 v[44:47], v[140:143], v[206:209], v[44:47]
	v_mfma_f32_16x16x32_bf16 v[40:43], v[168:171], v[206:209], v[40:43]
	v_mfma_f32_16x16x32_bf16 v[28:31], v[140:143], v[214:217], v[28:31]
	v_mfma_f32_16x16x32_bf16 v[24:27], v[168:171], v[214:217], v[24:27]
	v_mfma_f32_16x16x32_bf16 v[12:15], v[140:143], v[222:225], v[12:15]
	v_mfma_f32_16x16x32_bf16 v[8:11], v[168:171], v[222:225], v[8:11]
	v_mfma_f32_16x16x32_bf16 v[60:63], v[150:153], v[202:205], v[60:63]
	v_mfma_f32_16x16x32_bf16 v[56:59], v[172:175], v[202:205], v[56:59]
	v_mfma_f32_16x16x32_bf16 v[44:47], v[150:153], v[210:213], v[44:47]
	v_mfma_f32_16x16x32_bf16 v[40:43], v[172:175], v[210:213], v[40:43]
	v_mfma_f32_16x16x32_bf16 v[28:31], v[150:153], v[218:221], v[28:31]
	v_mfma_f32_16x16x32_bf16 v[24:27], v[172:175], v[218:221], v[24:27]
	v_mfma_f32_16x16x32_bf16 v[12:15], v[150:153], v[226:229], v[12:15]
	v_mfma_f32_16x16x32_bf16 v[8:11], v[172:175], v[226:229], v[8:11]
	s_setprio 0
	s_setprio 1
	v_mfma_f32_16x16x32_bf16 v[52:55], v[176:179], v[198:201], v[52:55]
	v_mfma_f32_16x16x32_bf16 v[48:51], v[184:187], v[198:201], v[48:51]
	v_mfma_f32_16x16x32_bf16 v[36:39], v[176:179], v[206:209], v[36:39]
	v_mfma_f32_16x16x32_bf16 v[32:35], v[184:187], v[206:209], v[32:35]
	v_mfma_f32_16x16x32_bf16 v[20:23], v[176:179], v[214:217], v[20:23]
	v_mfma_f32_16x16x32_bf16 v[16:19], v[184:187], v[214:217], v[16:19]
	v_mfma_f32_16x16x32_bf16 v[4:7], v[176:179], v[222:225], v[4:7]
	v_mfma_f32_16x16x32_bf16 v[0:3], v[184:187], v[222:225], v[0:3]
	v_mfma_f32_16x16x32_bf16 v[52:55], v[180:183], v[202:205], v[52:55]
	v_mfma_f32_16x16x32_bf16 v[48:51], v[188:191], v[202:205], v[48:51]
	v_mfma_f32_16x16x32_bf16 v[36:39], v[180:183], v[210:213], v[36:39]
	v_mfma_f32_16x16x32_bf16 v[32:35], v[188:191], v[210:213], v[32:35]
	v_mfma_f32_16x16x32_bf16 v[20:23], v[180:183], v[218:221], v[20:23]
	v_mfma_f32_16x16x32_bf16 v[16:19], v[188:191], v[218:221], v[16:19]
	v_mfma_f32_16x16x32_bf16 v[4:7], v[180:183], v[226:229], v[4:7]
	v_mfma_f32_16x16x32_bf16 v[0:3], v[188:191], v[226:229], v[0:3]
	s_setprio 0
	s_barrier
	s_add_i32 s64, s64, 2
	s_add_u32 s26, s26, 0x100
	s_addc_u32 s27, s27, 0
	s_add_u32 s60, s60, 0x100
	s_addc_u32 s61, s61, 0
	s_cmp_gt_u32 s64, 13
	s_cbranch_scc0 .LBB0_711
	s_and_b64 vcc, exec, s[16:17]
	s_cbranch_vccz .LBB0_714
	s_barrier
